# st1 prologue shifts the rv rows in place so the st1 epilogue reuses them without shifting (on top of the packed-conv st2 epilogue)
# speedup vs baseline: 1.0008x; 1.0008x over previous
; __device__ __forceinline__ float bf2f(u16 h){ return __uint_as_float(((unsigned)h)<<16); }
; __device__ __forceinline__ float hconv3(const u16* __restrict__ row, int t, float w0, float w1, float w2, float bias){
;   float m = bf2f(row[t]);
;   int mi=__float_as_int(m);
;   float l=__int_as_float(__builtin_amdgcn_update_dpp(0, mi, 0x138, 0xf, 0xf, false));
;   float r=__int_as_float(__builtin_amdgcn_update_dpp(0, mi, 0x130, 0xf, 0xf, false));
;   return w0*l+w1*m+w2*r+bias;
; }
; __device__ __forceinline__ void phase_hyena(KP kp_, int hf){ asm volatile("" : "+s"(kp_)); const Params p=load_params(kp_);
;     ...
;       else if (st==1){ int tq=tid; asm volatile("" : "+v"(tq));
;         _Pragma("unroll 4") for (int i=0;i<8;++i){ int t=tq+512*i;
;           float2 a0=make_float2(hconv3(rv,t,wv0,wv1,wv2,bv_), hconv3(rv+8192,t,wv0,wv1,wv2,bv_));
;           float2 a1=make_float2(hconv3(rv,t+4096,wv0,wv1,wv2,bv_), hconv3(rv+8192,t+4096,wv0,wv1,wv2,bv_));
;           fwd12_padded(Z,twA,twB,t,a0,a1); }
.LBB0_1324:
	s_and_b64 vcc, exec, s[12:13]
	s_cbranch_vccz .LBB0_1328
	v_lshlrev_b32_e32 v15, 1, v86
	v_add_u32_e32 v0, 0x0, v15
	v_add_u32_e32 v1, 0x4000, v15
	v_add_u32_e32 v2, 0x2000, v15
	v_add_u32_e32 v4, 0x6000, v15
	v_add_u32_e32 v5, 0x1000, v15
	v_add_u32_e32 v6, 0x5000, v15
	v_add_u32_e32 v7, 0x3000, v15
	v_add_u32_e32 v8, 0x7000, v15
	s_sub_u32 s12, s96, 0x2000000
	s_subb_u32 s13, s97, 0
	global_load_ushort v104, v0, s[12:13] offset:0
	global_load_ushort v105, v1, s[12:13] offset:0
	global_load_ushort v106, v2, s[12:13] offset:0
	global_load_ushort v107, v4, s[12:13] offset:0
	global_load_ushort v108, v0, s[12:13] offset:1024
	global_load_ushort v109, v1, s[12:13] offset:1024
	global_load_ushort v110, v2, s[12:13] offset:1024
	global_load_ushort v111, v4, s[12:13] offset:1024
	global_load_ushort v112, v0, s[12:13] offset:2048
	global_load_ushort v113, v1, s[12:13] offset:2048
	global_load_ushort v114, v2, s[12:13] offset:2048
	global_load_ushort v115, v4, s[12:13] offset:2048
	global_load_ushort v116, v0, s[12:13] offset:3072
	global_load_ushort v117, v1, s[12:13] offset:3072
	global_load_ushort v118, v2, s[12:13] offset:3072
	global_load_ushort v119, v4, s[12:13] offset:3072
	global_load_ushort v120, v5, s[12:13] offset:0
	global_load_ushort v121, v6, s[12:13] offset:0
	global_load_ushort v122, v7, s[12:13] offset:0
	global_load_ushort v123, v8, s[12:13] offset:0
	global_load_ushort v124, v5, s[12:13] offset:1024
	global_load_ushort v125, v6, s[12:13] offset:1024
	global_load_ushort v126, v7, s[12:13] offset:1024
	global_load_ushort v127, v8, s[12:13] offset:1024
	global_load_ushort v134, v5, s[12:13] offset:2048
	global_load_ushort v135, v6, s[12:13] offset:2048
	global_load_ushort v136, v7, s[12:13] offset:2048
	global_load_ushort v137, v8, s[12:13] offset:2048
	global_load_ushort v138, v5, s[12:13] offset:3072
	global_load_ushort v139, v6, s[12:13] offset:3072
	global_load_ushort v140, v7, s[12:13] offset:3072
	global_load_ushort v141, v8, s[12:13] offset:3072
	v_lshlrev_b32_e32 v12, 3, v86
	v_add_u32_e32 v13, 0x10000, v12
	v_lshrrev_b32_e32 v14, 6, v86
	v_lshl_add_u32 v14, v14, 3, s88
	v_and_b32_e32 v15, 63, v86
	v_lshl_add_u32 v15, v15, 3, s91
	ds_read_b64 v[10:11], v15
	ds_read_b64 v[58:59], v14 offset:0
	ds_read_b64 v[60:61], v14 offset:64
	ds_read_b64 v[62:63], v14 offset:128
	ds_read_b64 v[64:65], v14 offset:192
	ds_read_b64 v[66:67], v14 offset:256
	ds_read_b64 v[68:69], v14 offset:320
	ds_read_b64 v[70:71], v14 offset:384
	ds_read_b64 v[72:73], v14 offset:448
	s_waitcnt lgkmcnt(0)
	v_pk_mul_f32 v[222:223], v[58:59], v[10:11] op_sel:[1,1] op_sel_hi:[1,0]
	v_pk_fma_f32 v[22:23], v[58:59], v[10:11], v[222:223] op_sel:[0,0,0] op_sel_hi:[0,1,1] neg_lo:[0,0,1]
	v_pk_mul_f32 v[222:223], v[22:23], v[22:23] op_sel:[1,1] op_sel_hi:[1,0]
	v_pk_fma_f32 v[24:25], v[22:23], v[22:23], v[222:223] op_sel:[0,0,0] op_sel_hi:[0,1,1] neg_lo:[0,0,1]
	v_pk_mul_f32 v[222:223], v[24:25], v[22:23] op_sel:[1,1] op_sel_hi:[1,0]
	v_pk_fma_f32 v[26:27], v[24:25], v[22:23], v[222:223] op_sel:[0,0,0] op_sel_hi:[0,1,1] neg_lo:[0,0,1]
	s_waitcnt vmcnt(28)
	v_lshlrev_b32_e32 v104, 16, v104
	v_lshlrev_b32_e32 v105, 16, v105
	v_pk_mul_f32 v[82:83], v[34:35], v[104:105]
	v_fmac_f32_dpp v82, v104, v32 wave_shr:1 row_mask:0xf bank_mask:0xf
	v_fmac_f32_dpp v83, v105, v33 wave_shr:1 row_mask:0xf bank_mask:0xf
	v_fmac_f32_dpp v82, v104, v36 wave_shl:1 row_mask:0xf bank_mask:0xf
	v_fmac_f32_dpp v83, v105, v37 wave_shl:1 row_mask:0xf bank_mask:0xf
	v_pk_add_f32 v[28:29], v[38:39], v[82:83]
	v_lshlrev_b32_e32 v106, 16, v106
	v_lshlrev_b32_e32 v107, 16, v107
	v_pk_mul_f32 v[82:83], v[34:35], v[106:107]
	v_fmac_f32_dpp v82, v106, v32 wave_shr:1 row_mask:0xf bank_mask:0xf
	v_fmac_f32_dpp v83, v107, v33 wave_shr:1 row_mask:0xf bank_mask:0xf
	v_fmac_f32_dpp v82, v106, v36 wave_shl:1 row_mask:0xf bank_mask:0xf
	v_fmac_f32_dpp v83, v107, v37 wave_shl:1 row_mask:0xf bank_mask:0xf
	v_pk_add_f32 v[30:31], v[38:39], v[82:83]
	v_pk_add_f32 v[84:85], v[28:29], v[30:31]
	ds_write_b64 v12, v[84:85] offset:0
	v_pk_add_f32 v[74:75], v[28:29], v[30:31] op_sel:[0,1] op_sel_hi:[1,0] neg_hi:[0,1]
	v_pk_mul_f32 v[222:223], v[74:75], v[22:23] op_sel:[1,1] op_sel_hi:[1,0]
	v_pk_fma_f32 v[84:85], v[74:75], v[22:23], v[222:223] op_sel:[0,0,0] op_sel_hi:[0,1,1] neg_lo:[0,0,1]
	ds_write_b64 v12, v[84:85] offset:32768
	v_pk_add_f32 v[74:75], v[28:29], v[30:31] neg_lo:[0,1] neg_hi:[0,1]
	v_pk_mul_f32 v[222:223], v[74:75], v[24:25] op_sel:[1,1] op_sel_hi:[1,0]
	v_pk_fma_f32 v[84:85], v[74:75], v[24:25], v[222:223] op_sel:[0,0,0] op_sel_hi:[0,1,1] neg_lo:[0,0,1]
	ds_write_b64 v13, v[84:85] offset:0
	v_pk_add_f32 v[74:75], v[28:29], v[30:31] op_sel:[0,1] op_sel_hi:[1,0] neg_lo:[0,1]
	v_pk_mul_f32 v[222:223], v[74:75], v[26:27] op_sel:[1,1] op_sel_hi:[1,0]
	v_pk_fma_f32 v[84:85], v[74:75], v[26:27], v[222:223] op_sel:[0,0,0] op_sel_hi:[0,1,1] neg_lo:[0,0,1]
	ds_write_b64 v13, v[84:85] offset:32768
	v_pk_mul_f32 v[222:223], v[60:61], v[10:11] op_sel:[1,1] op_sel_hi:[1,0]
	v_pk_fma_f32 v[22:23], v[60:61], v[10:11], v[222:223] op_sel:[0,0,0] op_sel_hi:[0,1,1] neg_lo:[0,0,1]
	v_pk_mul_f32 v[222:223], v[22:23], v[22:23] op_sel:[1,1] op_sel_hi:[1,0]
	v_pk_fma_f32 v[24:25], v[22:23], v[22:23], v[222:223] op_sel:[0,0,0] op_sel_hi:[0,1,1] neg_lo:[0,0,1]
	v_pk_mul_f32 v[222:223], v[24:25], v[22:23] op_sel:[1,1] op_sel_hi:[1,0]
	v_pk_fma_f32 v[26:27], v[24:25], v[22:23], v[222:223] op_sel:[0,0,0] op_sel_hi:[0,1,1] neg_lo:[0,0,1]
	s_waitcnt vmcnt(24)
; HD float2 cmul(float2 a, float2 b){ return make_float2(a.x*b.x - a.y*b.y, a.x*b.y + a.y*b.x); }
; HD void fwd12_padded(float2* Z, const float2* twA, const float2* twB, int t, float2 a0, float2 a1){
;   float2 w1=cmul(twA[t>>6],twB[t&63]), w2=cmul(w1,w1), w3=cmul(w2,w1);
;   Z[t]=make_float2(a0.x+a1.x,a0.y+a1.y);
;   Z[t+4096]=cmul(make_float2(a0.x+a1.y,a0.y-a1.x),w1);
;   Z[t+8192]=cmul(make_float2(a0.x-a1.x,a0.y-a1.y),w2);
;   Z[t+12288]=cmul(make_float2(a0.x-a1.y,a0.y+a1.x),w3);
; }
; __device__ __forceinline__ void phase_hyena(KP kp_, int hf){ asm volatile("" : "+s"(kp_)); const Params p=load_params(kp_);
;     ...
;       else if (st==1){ int tq=tid; asm volatile("" : "+v"(tq));
;         _Pragma("unroll 4") for (int i=0;i<8;++i){ int t=tq+512*i;
;           float2 a0=make_float2(hconv3(rv,t,wv0,wv1,wv2,bv_), hconv3(rv+8192,t,wv0,wv1,wv2,bv_));
;           float2 a1=make_float2(hconv3(rv,t+4096,wv0,wv1,wv2,bv_), hconv3(rv+8192,t+4096,wv0,wv1,wv2,bv_));
;           fwd12_padded(Z,twA,twB,t,a0,a1); }
	v_lshlrev_b32_e32 v108, 16, v108
	v_lshlrev_b32_e32 v109, 16, v109
	v_pk_mul_f32 v[82:83], v[34:35], v[108:109]
	v_fmac_f32_dpp v82, v108, v32 wave_shr:1 row_mask:0xf bank_mask:0xf
	v_fmac_f32_dpp v83, v109, v33 wave_shr:1 row_mask:0xf bank_mask:0xf
	v_fmac_f32_dpp v82, v108, v36 wave_shl:1 row_mask:0xf bank_mask:0xf
	v_fmac_f32_dpp v83, v109, v37 wave_shl:1 row_mask:0xf bank_mask:0xf
	v_pk_add_f32 v[28:29], v[38:39], v[82:83]
	v_lshlrev_b32_e32 v110, 16, v110
	v_lshlrev_b32_e32 v111, 16, v111
	v_pk_mul_f32 v[82:83], v[34:35], v[110:111]
	v_fmac_f32_dpp v82, v110, v32 wave_shr:1 row_mask:0xf bank_mask:0xf
	v_fmac_f32_dpp v83, v111, v33 wave_shr:1 row_mask:0xf bank_mask:0xf
	v_fmac_f32_dpp v82, v110, v36 wave_shl:1 row_mask:0xf bank_mask:0xf
	v_fmac_f32_dpp v83, v111, v37 wave_shl:1 row_mask:0xf bank_mask:0xf
	v_pk_add_f32 v[30:31], v[38:39], v[82:83]
	v_pk_add_f32 v[84:85], v[28:29], v[30:31]
	ds_write_b64 v12, v[84:85] offset:4096
	v_pk_add_f32 v[74:75], v[28:29], v[30:31] op_sel:[0,1] op_sel_hi:[1,0] neg_hi:[0,1]
	v_pk_mul_f32 v[222:223], v[74:75], v[22:23] op_sel:[1,1] op_sel_hi:[1,0]
	v_pk_fma_f32 v[84:85], v[74:75], v[22:23], v[222:223] op_sel:[0,0,0] op_sel_hi:[0,1,1] neg_lo:[0,0,1]
	ds_write_b64 v12, v[84:85] offset:36864
	v_pk_add_f32 v[74:75], v[28:29], v[30:31] neg_lo:[0,1] neg_hi:[0,1]
	v_pk_mul_f32 v[222:223], v[74:75], v[24:25] op_sel:[1,1] op_sel_hi:[1,0]
	v_pk_fma_f32 v[84:85], v[74:75], v[24:25], v[222:223] op_sel:[0,0,0] op_sel_hi:[0,1,1] neg_lo:[0,0,1]
	ds_write_b64 v13, v[84:85] offset:4096
	v_pk_add_f32 v[74:75], v[28:29], v[30:31] op_sel:[0,1] op_sel_hi:[1,0] neg_lo:[0,1]
	v_pk_mul_f32 v[222:223], v[74:75], v[26:27] op_sel:[1,1] op_sel_hi:[1,0]
	v_pk_fma_f32 v[84:85], v[74:75], v[26:27], v[222:223] op_sel:[0,0,0] op_sel_hi:[0,1,1] neg_lo:[0,0,1]
	ds_write_b64 v13, v[84:85] offset:36864
	v_pk_mul_f32 v[222:223], v[62:63], v[10:11] op_sel:[1,1] op_sel_hi:[1,0]
	v_pk_fma_f32 v[22:23], v[62:63], v[10:11], v[222:223] op_sel:[0,0,0] op_sel_hi:[0,1,1] neg_lo:[0,0,1]
	v_pk_mul_f32 v[222:223], v[22:23], v[22:23] op_sel:[1,1] op_sel_hi:[1,0]
	v_pk_fma_f32 v[24:25], v[22:23], v[22:23], v[222:223] op_sel:[0,0,0] op_sel_hi:[0,1,1] neg_lo:[0,0,1]
	v_pk_mul_f32 v[222:223], v[24:25], v[22:23] op_sel:[1,1] op_sel_hi:[1,0]
	v_pk_fma_f32 v[26:27], v[24:25], v[22:23], v[222:223] op_sel:[0,0,0] op_sel_hi:[0,1,1] neg_lo:[0,0,1]
	s_waitcnt vmcnt(20)
	v_lshlrev_b32_e32 v112, 16, v112
	v_lshlrev_b32_e32 v113, 16, v113
	v_pk_mul_f32 v[82:83], v[34:35], v[112:113]
	v_fmac_f32_dpp v82, v112, v32 wave_shr:1 row_mask:0xf bank_mask:0xf
	v_fmac_f32_dpp v83, v113, v33 wave_shr:1 row_mask:0xf bank_mask:0xf
	v_fmac_f32_dpp v82, v112, v36 wave_shl:1 row_mask:0xf bank_mask:0xf
	v_fmac_f32_dpp v83, v113, v37 wave_shl:1 row_mask:0xf bank_mask:0xf
	v_pk_add_f32 v[28:29], v[38:39], v[82:83]
	v_lshlrev_b32_e32 v114, 16, v114
	v_lshlrev_b32_e32 v115, 16, v115
	v_pk_mul_f32 v[82:83], v[34:35], v[114:115]
	v_fmac_f32_dpp v82, v114, v32 wave_shr:1 row_mask:0xf bank_mask:0xf
	v_fmac_f32_dpp v83, v115, v33 wave_shr:1 row_mask:0xf bank_mask:0xf
	v_fmac_f32_dpp v82, v114, v36 wave_shl:1 row_mask:0xf bank_mask:0xf
	v_fmac_f32_dpp v83, v115, v37 wave_shl:1 row_mask:0xf bank_mask:0xf
	v_pk_add_f32 v[30:31], v[38:39], v[82:83]
	v_pk_add_f32 v[84:85], v[28:29], v[30:31]
	ds_write_b64 v12, v[84:85] offset:8192
	v_pk_add_f32 v[74:75], v[28:29], v[30:31] op_sel:[0,1] op_sel_hi:[1,0] neg_hi:[0,1]
	v_pk_mul_f32 v[222:223], v[74:75], v[22:23] op_sel:[1,1] op_sel_hi:[1,0]
	v_pk_fma_f32 v[84:85], v[74:75], v[22:23], v[222:223] op_sel:[0,0,0] op_sel_hi:[0,1,1] neg_lo:[0,0,1]
	ds_write_b64 v12, v[84:85] offset:40960
	v_pk_add_f32 v[74:75], v[28:29], v[30:31] neg_lo:[0,1] neg_hi:[0,1]
	v_pk_mul_f32 v[222:223], v[74:75], v[24:25] op_sel:[1,1] op_sel_hi:[1,0]
	v_pk_fma_f32 v[84:85], v[74:75], v[24:25], v[222:223] op_sel:[0,0,0] op_sel_hi:[0,1,1] neg_lo:[0,0,1]
	ds_write_b64 v13, v[84:85] offset:8192
	v_pk_add_f32 v[74:75], v[28:29], v[30:31] op_sel:[0,1] op_sel_hi:[1,0] neg_lo:[0,1]
	v_pk_mul_f32 v[222:223], v[74:75], v[26:27] op_sel:[1,1] op_sel_hi:[1,0]
	v_pk_fma_f32 v[84:85], v[74:75], v[26:27], v[222:223] op_sel:[0,0,0] op_sel_hi:[0,1,1] neg_lo:[0,0,1]
	ds_write_b64 v13, v[84:85] offset:40960
	v_pk_mul_f32 v[222:223], v[64:65], v[10:11] op_sel:[1,1] op_sel_hi:[1,0]
	v_pk_fma_f32 v[22:23], v[64:65], v[10:11], v[222:223] op_sel:[0,0,0] op_sel_hi:[0,1,1] neg_lo:[0,0,1]
	v_pk_mul_f32 v[222:223], v[22:23], v[22:23] op_sel:[1,1] op_sel_hi:[1,0]
	v_pk_fma_f32 v[24:25], v[22:23], v[22:23], v[222:223] op_sel:[0,0,0] op_sel_hi:[0,1,1] neg_lo:[0,0,1]
	v_pk_mul_f32 v[222:223], v[24:25], v[22:23] op_sel:[1,1] op_sel_hi:[1,0]
	v_pk_fma_f32 v[26:27], v[24:25], v[22:23], v[222:223] op_sel:[0,0,0] op_sel_hi:[0,1,1] neg_lo:[0,0,1]
	s_waitcnt vmcnt(16)
; HD float2 cmul(float2 a, float2 b){ return make_float2(a.x*b.x - a.y*b.y, a.x*b.y + a.y*b.x); }
; HD void fwd12_padded(float2* Z, const float2* twA, const float2* twB, int t, float2 a0, float2 a1){
;   float2 w1=cmul(twA[t>>6],twB[t&63]), w2=cmul(w1,w1), w3=cmul(w2,w1);
;   Z[t]=make_float2(a0.x+a1.x,a0.y+a1.y);
;   Z[t+4096]=cmul(make_float2(a0.x+a1.y,a0.y-a1.x),w1);
;   Z[t+8192]=cmul(make_float2(a0.x-a1.x,a0.y-a1.y),w2);
;   Z[t+12288]=cmul(make_float2(a0.x-a1.y,a0.y+a1.x),w3);
; }
; __device__ __forceinline__ void phase_hyena(KP kp_, int hf){ asm volatile("" : "+s"(kp_)); const Params p=load_params(kp_);
;     ...
;       else if (st==1){ int tq=tid; asm volatile("" : "+v"(tq));
;         _Pragma("unroll 4") for (int i=0;i<8;++i){ int t=tq+512*i;
;           float2 a0=make_float2(hconv3(rv,t,wv0,wv1,wv2,bv_), hconv3(rv+8192,t,wv0,wv1,wv2,bv_));
;           float2 a1=make_float2(hconv3(rv,t+4096,wv0,wv1,wv2,bv_), hconv3(rv+8192,t+4096,wv0,wv1,wv2,bv_));
;           fwd12_padded(Z,twA,twB,t,a0,a1); }
	v_lshlrev_b32_e32 v116, 16, v116
	v_lshlrev_b32_e32 v117, 16, v117
	v_pk_mul_f32 v[82:83], v[34:35], v[116:117]
	v_fmac_f32_dpp v82, v116, v32 wave_shr:1 row_mask:0xf bank_mask:0xf
	v_fmac_f32_dpp v83, v117, v33 wave_shr:1 row_mask:0xf bank_mask:0xf
	v_fmac_f32_dpp v82, v116, v36 wave_shl:1 row_mask:0xf bank_mask:0xf
	v_fmac_f32_dpp v83, v117, v37 wave_shl:1 row_mask:0xf bank_mask:0xf
	v_pk_add_f32 v[28:29], v[38:39], v[82:83]
	v_lshlrev_b32_e32 v118, 16, v118
	v_lshlrev_b32_e32 v119, 16, v119
	v_pk_mul_f32 v[82:83], v[34:35], v[118:119]
	v_fmac_f32_dpp v82, v118, v32 wave_shr:1 row_mask:0xf bank_mask:0xf
	v_fmac_f32_dpp v83, v119, v33 wave_shr:1 row_mask:0xf bank_mask:0xf
	v_fmac_f32_dpp v82, v118, v36 wave_shl:1 row_mask:0xf bank_mask:0xf
	v_fmac_f32_dpp v83, v119, v37 wave_shl:1 row_mask:0xf bank_mask:0xf
	v_pk_add_f32 v[30:31], v[38:39], v[82:83]
	v_pk_add_f32 v[84:85], v[28:29], v[30:31]
	ds_write_b64 v12, v[84:85] offset:12288
	v_pk_add_f32 v[74:75], v[28:29], v[30:31] op_sel:[0,1] op_sel_hi:[1,0] neg_hi:[0,1]
	v_pk_mul_f32 v[222:223], v[74:75], v[22:23] op_sel:[1,1] op_sel_hi:[1,0]
	v_pk_fma_f32 v[84:85], v[74:75], v[22:23], v[222:223] op_sel:[0,0,0] op_sel_hi:[0,1,1] neg_lo:[0,0,1]
	ds_write_b64 v12, v[84:85] offset:45056
	v_pk_add_f32 v[74:75], v[28:29], v[30:31] neg_lo:[0,1] neg_hi:[0,1]
	v_pk_mul_f32 v[222:223], v[74:75], v[24:25] op_sel:[1,1] op_sel_hi:[1,0]
	v_pk_fma_f32 v[84:85], v[74:75], v[24:25], v[222:223] op_sel:[0,0,0] op_sel_hi:[0,1,1] neg_lo:[0,0,1]
	ds_write_b64 v13, v[84:85] offset:12288
	v_pk_add_f32 v[74:75], v[28:29], v[30:31] op_sel:[0,1] op_sel_hi:[1,0] neg_lo:[0,1]
	v_pk_mul_f32 v[222:223], v[74:75], v[26:27] op_sel:[1,1] op_sel_hi:[1,0]
	v_pk_fma_f32 v[84:85], v[74:75], v[26:27], v[222:223] op_sel:[0,0,0] op_sel_hi:[0,1,1] neg_lo:[0,0,1]
	ds_write_b64 v13, v[84:85] offset:45056
	v_pk_mul_f32 v[222:223], v[66:67], v[10:11] op_sel:[1,1] op_sel_hi:[1,0]
	v_pk_fma_f32 v[22:23], v[66:67], v[10:11], v[222:223] op_sel:[0,0,0] op_sel_hi:[0,1,1] neg_lo:[0,0,1]
	v_pk_mul_f32 v[222:223], v[22:23], v[22:23] op_sel:[1,1] op_sel_hi:[1,0]
	v_pk_fma_f32 v[24:25], v[22:23], v[22:23], v[222:223] op_sel:[0,0,0] op_sel_hi:[0,1,1] neg_lo:[0,0,1]
	v_pk_mul_f32 v[222:223], v[24:25], v[22:23] op_sel:[1,1] op_sel_hi:[1,0]
	v_pk_fma_f32 v[26:27], v[24:25], v[22:23], v[222:223] op_sel:[0,0,0] op_sel_hi:[0,1,1] neg_lo:[0,0,1]
	s_waitcnt vmcnt(12)
	v_lshlrev_b32_e32 v120, 16, v120
	v_lshlrev_b32_e32 v121, 16, v121
	v_pk_mul_f32 v[82:83], v[34:35], v[120:121]
	v_fmac_f32_dpp v82, v120, v32 wave_shr:1 row_mask:0xf bank_mask:0xf
	v_fmac_f32_dpp v83, v121, v33 wave_shr:1 row_mask:0xf bank_mask:0xf
	v_fmac_f32_dpp v82, v120, v36 wave_shl:1 row_mask:0xf bank_mask:0xf
	v_fmac_f32_dpp v83, v121, v37 wave_shl:1 row_mask:0xf bank_mask:0xf
	v_pk_add_f32 v[28:29], v[38:39], v[82:83]
	v_lshlrev_b32_e32 v122, 16, v122
	v_lshlrev_b32_e32 v123, 16, v123
	v_pk_mul_f32 v[82:83], v[34:35], v[122:123]
	v_fmac_f32_dpp v82, v122, v32 wave_shr:1 row_mask:0xf bank_mask:0xf
	v_fmac_f32_dpp v83, v123, v33 wave_shr:1 row_mask:0xf bank_mask:0xf
	v_fmac_f32_dpp v82, v122, v36 wave_shl:1 row_mask:0xf bank_mask:0xf
	v_fmac_f32_dpp v83, v123, v37 wave_shl:1 row_mask:0xf bank_mask:0xf
	v_pk_add_f32 v[30:31], v[38:39], v[82:83]
	v_pk_add_f32 v[84:85], v[28:29], v[30:31]
	ds_write_b64 v12, v[84:85] offset:16384
	v_pk_add_f32 v[74:75], v[28:29], v[30:31] op_sel:[0,1] op_sel_hi:[1,0] neg_hi:[0,1]
	v_pk_mul_f32 v[222:223], v[74:75], v[22:23] op_sel:[1,1] op_sel_hi:[1,0]
	v_pk_fma_f32 v[84:85], v[74:75], v[22:23], v[222:223] op_sel:[0,0,0] op_sel_hi:[0,1,1] neg_lo:[0,0,1]
	ds_write_b64 v12, v[84:85] offset:49152
	v_pk_add_f32 v[74:75], v[28:29], v[30:31] neg_lo:[0,1] neg_hi:[0,1]
	v_pk_mul_f32 v[222:223], v[74:75], v[24:25] op_sel:[1,1] op_sel_hi:[1,0]
	v_pk_fma_f32 v[84:85], v[74:75], v[24:25], v[222:223] op_sel:[0,0,0] op_sel_hi:[0,1,1] neg_lo:[0,0,1]
	ds_write_b64 v13, v[84:85] offset:16384
	v_pk_add_f32 v[74:75], v[28:29], v[30:31] op_sel:[0,1] op_sel_hi:[1,0] neg_lo:[0,1]
	v_pk_mul_f32 v[222:223], v[74:75], v[26:27] op_sel:[1,1] op_sel_hi:[1,0]
	v_pk_fma_f32 v[84:85], v[74:75], v[26:27], v[222:223] op_sel:[0,0,0] op_sel_hi:[0,1,1] neg_lo:[0,0,1]
	ds_write_b64 v13, v[84:85] offset:49152
	v_pk_mul_f32 v[222:223], v[68:69], v[10:11] op_sel:[1,1] op_sel_hi:[1,0]
	v_pk_fma_f32 v[22:23], v[68:69], v[10:11], v[222:223] op_sel:[0,0,0] op_sel_hi:[0,1,1] neg_lo:[0,0,1]
	v_pk_mul_f32 v[222:223], v[22:23], v[22:23] op_sel:[1,1] op_sel_hi:[1,0]
	v_pk_fma_f32 v[24:25], v[22:23], v[22:23], v[222:223] op_sel:[0,0,0] op_sel_hi:[0,1,1] neg_lo:[0,0,1]
	v_pk_mul_f32 v[222:223], v[24:25], v[22:23] op_sel:[1,1] op_sel_hi:[1,0]
	v_pk_fma_f32 v[26:27], v[24:25], v[22:23], v[222:223] op_sel:[0,0,0] op_sel_hi:[0,1,1] neg_lo:[0,0,1]
	s_waitcnt vmcnt(8)
; HD float2 cmul(float2 a, float2 b){ return make_float2(a.x*b.x - a.y*b.y, a.x*b.y + a.y*b.x); }
; HD void fwd12_padded(float2* Z, const float2* twA, const float2* twB, int t, float2 a0, float2 a1){
;   float2 w1=cmul(twA[t>>6],twB[t&63]), w2=cmul(w1,w1), w3=cmul(w2,w1);
;   Z[t]=make_float2(a0.x+a1.x,a0.y+a1.y);
;   Z[t+4096]=cmul(make_float2(a0.x+a1.y,a0.y-a1.x),w1);
;   Z[t+8192]=cmul(make_float2(a0.x-a1.x,a0.y-a1.y),w2);
;   Z[t+12288]=cmul(make_float2(a0.x-a1.y,a0.y+a1.x),w3);
; }
; __device__ __forceinline__ void phase_hyena(KP kp_, int hf){ asm volatile("" : "+s"(kp_)); const Params p=load_params(kp_);
;     ...
;       else if (st==1){ int tq=tid; asm volatile("" : "+v"(tq));
;         _Pragma("unroll 4") for (int i=0;i<8;++i){ int t=tq+512*i;
;           float2 a0=make_float2(hconv3(rv,t,wv0,wv1,wv2,bv_), hconv3(rv+8192,t,wv0,wv1,wv2,bv_));
;           float2 a1=make_float2(hconv3(rv,t+4096,wv0,wv1,wv2,bv_), hconv3(rv+8192,t+4096,wv0,wv1,wv2,bv_));
;           fwd12_padded(Z,twA,twB,t,a0,a1); }
;         __syncthreads();
	v_lshlrev_b32_e32 v124, 16, v124
	v_lshlrev_b32_e32 v125, 16, v125
	v_pk_mul_f32 v[82:83], v[34:35], v[124:125]
	v_fmac_f32_dpp v82, v124, v32 wave_shr:1 row_mask:0xf bank_mask:0xf
	v_fmac_f32_dpp v83, v125, v33 wave_shr:1 row_mask:0xf bank_mask:0xf
	v_fmac_f32_dpp v82, v124, v36 wave_shl:1 row_mask:0xf bank_mask:0xf
	v_fmac_f32_dpp v83, v125, v37 wave_shl:1 row_mask:0xf bank_mask:0xf
	v_pk_add_f32 v[28:29], v[38:39], v[82:83]
	v_lshlrev_b32_e32 v126, 16, v126
	v_lshlrev_b32_e32 v127, 16, v127
	v_pk_mul_f32 v[82:83], v[34:35], v[126:127]
	v_fmac_f32_dpp v82, v126, v32 wave_shr:1 row_mask:0xf bank_mask:0xf
	v_fmac_f32_dpp v83, v127, v33 wave_shr:1 row_mask:0xf bank_mask:0xf
	v_fmac_f32_dpp v82, v126, v36 wave_shl:1 row_mask:0xf bank_mask:0xf
	v_fmac_f32_dpp v83, v127, v37 wave_shl:1 row_mask:0xf bank_mask:0xf
	v_pk_add_f32 v[30:31], v[38:39], v[82:83]
	v_pk_add_f32 v[84:85], v[28:29], v[30:31]
	ds_write_b64 v12, v[84:85] offset:20480
	v_pk_add_f32 v[74:75], v[28:29], v[30:31] op_sel:[0,1] op_sel_hi:[1,0] neg_hi:[0,1]
	v_pk_mul_f32 v[222:223], v[74:75], v[22:23] op_sel:[1,1] op_sel_hi:[1,0]
	v_pk_fma_f32 v[84:85], v[74:75], v[22:23], v[222:223] op_sel:[0,0,0] op_sel_hi:[0,1,1] neg_lo:[0,0,1]
	ds_write_b64 v12, v[84:85] offset:53248
	v_pk_add_f32 v[74:75], v[28:29], v[30:31] neg_lo:[0,1] neg_hi:[0,1]
	v_pk_mul_f32 v[222:223], v[74:75], v[24:25] op_sel:[1,1] op_sel_hi:[1,0]
	v_pk_fma_f32 v[84:85], v[74:75], v[24:25], v[222:223] op_sel:[0,0,0] op_sel_hi:[0,1,1] neg_lo:[0,0,1]
	ds_write_b64 v13, v[84:85] offset:20480
	v_pk_add_f32 v[74:75], v[28:29], v[30:31] op_sel:[0,1] op_sel_hi:[1,0] neg_lo:[0,1]
	v_pk_mul_f32 v[222:223], v[74:75], v[26:27] op_sel:[1,1] op_sel_hi:[1,0]
	v_pk_fma_f32 v[84:85], v[74:75], v[26:27], v[222:223] op_sel:[0,0,0] op_sel_hi:[0,1,1] neg_lo:[0,0,1]
	ds_write_b64 v13, v[84:85] offset:53248
	v_pk_mul_f32 v[222:223], v[70:71], v[10:11] op_sel:[1,1] op_sel_hi:[1,0]
	v_pk_fma_f32 v[22:23], v[70:71], v[10:11], v[222:223] op_sel:[0,0,0] op_sel_hi:[0,1,1] neg_lo:[0,0,1]
	v_pk_mul_f32 v[222:223], v[22:23], v[22:23] op_sel:[1,1] op_sel_hi:[1,0]
	v_pk_fma_f32 v[24:25], v[22:23], v[22:23], v[222:223] op_sel:[0,0,0] op_sel_hi:[0,1,1] neg_lo:[0,0,1]
	v_pk_mul_f32 v[222:223], v[24:25], v[22:23] op_sel:[1,1] op_sel_hi:[1,0]
	v_pk_fma_f32 v[26:27], v[24:25], v[22:23], v[222:223] op_sel:[0,0,0] op_sel_hi:[0,1,1] neg_lo:[0,0,1]
	s_waitcnt vmcnt(4)
	v_lshlrev_b32_e32 v134, 16, v134
	v_lshlrev_b32_e32 v135, 16, v135
	v_pk_mul_f32 v[82:83], v[34:35], v[134:135]
	v_fmac_f32_dpp v82, v134, v32 wave_shr:1 row_mask:0xf bank_mask:0xf
	v_fmac_f32_dpp v83, v135, v33 wave_shr:1 row_mask:0xf bank_mask:0xf
	v_fmac_f32_dpp v82, v134, v36 wave_shl:1 row_mask:0xf bank_mask:0xf
	v_fmac_f32_dpp v83, v135, v37 wave_shl:1 row_mask:0xf bank_mask:0xf
	v_pk_add_f32 v[28:29], v[38:39], v[82:83]
	v_lshlrev_b32_e32 v136, 16, v136
	v_lshlrev_b32_e32 v137, 16, v137
	v_pk_mul_f32 v[82:83], v[34:35], v[136:137]
	v_fmac_f32_dpp v82, v136, v32 wave_shr:1 row_mask:0xf bank_mask:0xf
	v_fmac_f32_dpp v83, v137, v33 wave_shr:1 row_mask:0xf bank_mask:0xf
	v_fmac_f32_dpp v82, v136, v36 wave_shl:1 row_mask:0xf bank_mask:0xf
	v_fmac_f32_dpp v83, v137, v37 wave_shl:1 row_mask:0xf bank_mask:0xf
	v_pk_add_f32 v[30:31], v[38:39], v[82:83]
	v_pk_add_f32 v[84:85], v[28:29], v[30:31]
	ds_write_b64 v12, v[84:85] offset:24576
	v_pk_add_f32 v[74:75], v[28:29], v[30:31] op_sel:[0,1] op_sel_hi:[1,0] neg_hi:[0,1]
	v_pk_mul_f32 v[222:223], v[74:75], v[22:23] op_sel:[1,1] op_sel_hi:[1,0]
	v_pk_fma_f32 v[84:85], v[74:75], v[22:23], v[222:223] op_sel:[0,0,0] op_sel_hi:[0,1,1] neg_lo:[0,0,1]
	ds_write_b64 v12, v[84:85] offset:57344
	v_pk_add_f32 v[74:75], v[28:29], v[30:31] neg_lo:[0,1] neg_hi:[0,1]
	v_pk_mul_f32 v[222:223], v[74:75], v[24:25] op_sel:[1,1] op_sel_hi:[1,0]
	v_pk_fma_f32 v[84:85], v[74:75], v[24:25], v[222:223] op_sel:[0,0,0] op_sel_hi:[0,1,1] neg_lo:[0,0,1]
	ds_write_b64 v13, v[84:85] offset:24576
	v_pk_add_f32 v[74:75], v[28:29], v[30:31] op_sel:[0,1] op_sel_hi:[1,0] neg_lo:[0,1]
	v_pk_mul_f32 v[222:223], v[74:75], v[26:27] op_sel:[1,1] op_sel_hi:[1,0]
	v_pk_fma_f32 v[84:85], v[74:75], v[26:27], v[222:223] op_sel:[0,0,0] op_sel_hi:[0,1,1] neg_lo:[0,0,1]
	ds_write_b64 v13, v[84:85] offset:57344
	v_pk_mul_f32 v[222:223], v[72:73], v[10:11] op_sel:[1,1] op_sel_hi:[1,0]
	v_pk_fma_f32 v[22:23], v[72:73], v[10:11], v[222:223] op_sel:[0,0,0] op_sel_hi:[0,1,1] neg_lo:[0,0,1]
	v_pk_mul_f32 v[222:223], v[22:23], v[22:23] op_sel:[1,1] op_sel_hi:[1,0]
	v_pk_fma_f32 v[24:25], v[22:23], v[22:23], v[222:223] op_sel:[0,0,0] op_sel_hi:[0,1,1] neg_lo:[0,0,1]
	v_pk_mul_f32 v[222:223], v[24:25], v[22:23] op_sel:[1,1] op_sel_hi:[1,0]
	v_pk_fma_f32 v[26:27], v[24:25], v[22:23], v[222:223] op_sel:[0,0,0] op_sel_hi:[0,1,1] neg_lo:[0,0,1]
	s_waitcnt vmcnt(0)
	v_lshlrev_b32_e32 v138, 16, v138
	v_lshlrev_b32_e32 v139, 16, v139
	v_pk_mul_f32 v[82:83], v[34:35], v[138:139]
	v_fmac_f32_dpp v82, v138, v32 wave_shr:1 row_mask:0xf bank_mask:0xf
	v_fmac_f32_dpp v83, v139, v33 wave_shr:1 row_mask:0xf bank_mask:0xf
	v_fmac_f32_dpp v82, v138, v36 wave_shl:1 row_mask:0xf bank_mask:0xf
	v_fmac_f32_dpp v83, v139, v37 wave_shl:1 row_mask:0xf bank_mask:0xf
	v_pk_add_f32 v[28:29], v[38:39], v[82:83]
	v_lshlrev_b32_e32 v140, 16, v140
	v_lshlrev_b32_e32 v141, 16, v141
	v_pk_mul_f32 v[82:83], v[34:35], v[140:141]
	v_fmac_f32_dpp v82, v140, v32 wave_shr:1 row_mask:0xf bank_mask:0xf
	v_fmac_f32_dpp v83, v141, v33 wave_shr:1 row_mask:0xf bank_mask:0xf
	v_fmac_f32_dpp v82, v140, v36 wave_shl:1 row_mask:0xf bank_mask:0xf
	v_fmac_f32_dpp v83, v141, v37 wave_shl:1 row_mask:0xf bank_mask:0xf
	v_pk_add_f32 v[30:31], v[38:39], v[82:83]
	v_pk_add_f32 v[84:85], v[28:29], v[30:31]
	ds_write_b64 v12, v[84:85] offset:28672
	v_pk_add_f32 v[74:75], v[28:29], v[30:31] op_sel:[0,1] op_sel_hi:[1,0] neg_hi:[0,1]
	v_pk_mul_f32 v[222:223], v[74:75], v[22:23] op_sel:[1,1] op_sel_hi:[1,0]
	v_pk_fma_f32 v[84:85], v[74:75], v[22:23], v[222:223] op_sel:[0,0,0] op_sel_hi:[0,1,1] neg_lo:[0,0,1]
	ds_write_b64 v12, v[84:85] offset:61440
	v_pk_add_f32 v[74:75], v[28:29], v[30:31] neg_lo:[0,1] neg_hi:[0,1]
	v_pk_mul_f32 v[222:223], v[74:75], v[24:25] op_sel:[1,1] op_sel_hi:[1,0]
	v_pk_fma_f32 v[84:85], v[74:75], v[24:25], v[222:223] op_sel:[0,0,0] op_sel_hi:[0,1,1] neg_lo:[0,0,1]
	ds_write_b64 v13, v[84:85] offset:28672
	v_pk_add_f32 v[74:75], v[28:29], v[30:31] op_sel:[0,1] op_sel_hi:[1,0] neg_lo:[0,1]
	v_pk_mul_f32 v[222:223], v[74:75], v[26:27] op_sel:[1,1] op_sel_hi:[1,0]
	v_pk_fma_f32 v[84:85], v[74:75], v[26:27], v[222:223] op_sel:[0,0,0] op_sel_hi:[0,1,1] neg_lo:[0,0,1]
	ds_write_b64 v13, v[84:85] offset:61440
	s_mov_b32 s50, 0x2000
	s_mov_b32 s51, 0
	s_waitcnt lgkmcnt(0)
	s_barrier

; HD float2 cmul(float2 a, float2 b){ return make_float2(a.x*b.x - a.y*b.y, a.x*b.y + a.y*b.x); }
; HD float2 cmulc(float2 a, float2 b){ return make_float2(a.x*b.x + a.y*b.y, a.y*b.x - a.x*b.y); }
; HD void inv12_half(const float2* Z, const float2* twA, const float2* twB, int t, float2& x0, float2& x1){
;   float2 w1=cmul(twA[t>>6],twB[t&63]), w2=cmul(w1,w1), w3=cmul(w2,w1);
;   float2 b0=Z[t], b1=cmulc(Z[t+4096],w1), b2=cmulc(Z[t+8192],w2), b3=cmulc(Z[t+12288],w3);
;   float2 s02=make_float2(b0.x+b2.x,b0.y+b2.y), d02=make_float2(b0.x-b2.x,b0.y-b2.y);
;   float2 s13=make_float2(b1.x+b3.x,b1.y+b3.y), d13=make_float2(b1.x-b3.x,b1.y-b3.y);
;   x0=make_float2(s02.x+s13.x,s02.y+s13.y);
;   x1=make_float2(d02.x-d13.y,d02.y+d13.x);
; }
; __device__ __forceinline__ void phase_hyena(KP kp_, int hf){ asm volatile("" : "+s"(kp_)); const Params p=load_params(kp_);
;     ...
;         if (st==1){ int tq=tid; asm volatile("" : "+v"(tq));
;           _Pragma("unroll 4") for (int i=0;i<8;++i){ int tb=tq+512*i; float2 xr[2]; inv12_half(Z,twA,twB,tb,xr[0],xr[1]);
;             _Pragma("unroll") for (int hh=0;hh<2;++hh){ int t=tb+hh*4096;
;               float u0=hconv3(rv,t,wv0,wv1,wv2,bv_), u1=hconv3(rv+8192,t,wv0,wv1,wv2,bv_);
;               float x0=hconv3(r1,t,wa0,wa1,wa2,ba_), x1=hconv3(r1+8192,t,wa0,wa1,wa2,ba_);
;               float2 y=xr[hh]; y.x*=(1.f/16384.f); y.y*=(1.f/16384.f);
;               Zs[t]=make_float2(x0*(y.x+u0*bias0), x1*(y.y+u1*bias0)); } }
.LBB0_1340:
	s_and_b64 vcc, exec, s[12:13]
	s_cbranch_vccz .LBB0_1343
	v_lshlrev_b32_e32 v6, 1, v86
	v_add_u32_e32 v142, 0x1000000, v6
	v_add_u32_e32 v143, 0x1001000, v6
	v_add_u32_e32 v144, 0x1002000, v6
	v_add_u32_e32 v145, 0x1003000, v6
	v_add_u32_e32 v150, 0x1004000, v6
	v_add_u32_e32 v151, 0x1005000, v6
	v_add_u32_e32 v152, 0x1006000, v6
	v_add_u32_e32 v153, 0x1007000, v6
	v_lshlrev_b32_e32 v5, 3, v86
	v_mov_b32_e32 v8, v5
	v_add_u32_e32 v9, 0x10000, v5
	v_lshrrev_b32_e32 v7, 6, v86
	v_lshl_add_u32 v7, v7, 3, s88
	v_and_b32_e32 v6, 63, v86
	v_lshl_add_u32 v6, v6, 3, s91
	ds_read_b64 v[10:11], v6
	s_sub_u32 s12, s96, 0x2000000
	s_subb_u32 s13, s97, 0
	global_load_ushort v230, v142, s[12:13] offset:0
	global_load_ushort v231, v150, s[12:13] offset:0
	global_load_ushort v234, v144, s[12:13] offset:0
	global_load_ushort v235, v152, s[12:13] offset:0
	ds_read_b64 v[12:13], v7 offset:0
	ds_read_b64 v[14:15], v8 offset:0
	ds_read_b64 v[16:17], v8 offset:32768
	ds_read_b64 v[18:19], v9 offset:0
	ds_read_b64 v[20:21], v9 offset:32768
	global_load_ushort v242, v142, s[12:13] offset:1024
	global_load_ushort v243, v150, s[12:13] offset:1024
	global_load_ushort v246, v144, s[12:13] offset:1024
	global_load_ushort v247, v152, s[12:13] offset:1024
	ds_read_b64 v[58:59], v7 offset:64
	ds_read_b64 v[60:61], v8 offset:4096
	ds_read_b64 v[62:63], v8 offset:36864
	ds_read_b64 v[64:65], v9 offset:4096
	ds_read_b64 v[66:67], v9 offset:36864
	s_waitcnt lgkmcnt(5)
	v_pk_mul_f32 v[222:223], v[12:13], v[10:11] op_sel:[1,1] op_sel_hi:[1,0]
	v_pk_fma_f32 v[22:23], v[12:13], v[10:11], v[222:223] op_sel:[0,0,0] op_sel_hi:[0,1,1] neg_lo:[0,0,1]
	v_pk_mul_f32 v[222:223], v[22:23], v[22:23] op_sel:[1,1] op_sel_hi:[1,0]
	v_pk_fma_f32 v[24:25], v[22:23], v[22:23], v[222:223] op_sel:[0,0,0] op_sel_hi:[0,1,1] neg_lo:[0,0,1]
	v_pk_mul_f32 v[222:223], v[24:25], v[22:23] op_sel:[1,1] op_sel_hi:[1,0]
	v_pk_fma_f32 v[26:27], v[24:25], v[22:23], v[222:223] op_sel:[0,0,0] op_sel_hi:[0,1,1] neg_lo:[0,0,1]
	v_pk_mul_f32 v[222:223], v[16:17], v[22:23] op_sel:[1,1] op_sel_hi:[0,1]
	v_pk_fma_f32 v[28:29], v[16:17], v[22:23], v[222:223] op_sel:[0,0,0] op_sel_hi:[1,0,1] neg_hi:[0,0,1]
	v_pk_mul_f32 v[222:223], v[18:19], v[24:25] op_sel:[1,1] op_sel_hi:[0,1]
	v_pk_fma_f32 v[30:31], v[18:19], v[24:25], v[222:223] op_sel:[0,0,0] op_sel_hi:[1,0,1] neg_hi:[0,0,1]
	v_pk_mul_f32 v[222:223], v[20:21], v[26:27] op_sel:[1,1] op_sel_hi:[0,1]
	v_pk_fma_f32 v[68:69], v[20:21], v[26:27], v[222:223] op_sel:[0,0,0] op_sel_hi:[1,0,1] neg_hi:[0,0,1]
	v_pk_add_f32 v[70:71], v[14:15], v[30:31]
	v_pk_add_f32 v[72:73], v[14:15], v[30:31] neg_lo:[0,1] neg_hi:[0,1]
	v_pk_add_f32 v[74:75], v[28:29], v[68:69]
	v_pk_add_f32 v[80:81], v[28:29], v[68:69] neg_lo:[0,1] neg_hi:[0,1]
	v_pk_add_f32 v[82:83], v[70:71], v[74:75]
	v_pk_add_f32 v[84:85], v[72:73], v[80:81] op_sel:[0,1] op_sel_hi:[1,0] neg_lo:[0,1]
	s_waitcnt vmcnt(4)
	v_pk_mul_f32 v[172:173], v[34:35], v[104:105]
	v_fmac_f32_dpp v172, v104, v32 wave_shr:1 row_mask:0xf bank_mask:0xf
	v_fmac_f32_dpp v173, v105, v33 wave_shr:1 row_mask:0xf bank_mask:0xf
	v_fmac_f32_dpp v172, v104, v36 wave_shl:1 row_mask:0xf bank_mask:0xf
	v_fmac_f32_dpp v173, v105, v37 wave_shl:1 row_mask:0xf bank_mask:0xf
	v_pk_add_f32 v[174:175], v[38:39], v[172:173]
	v_lshlrev_b32_e32 v224, 16, v230
	v_lshlrev_b32_e32 v225, 16, v231
	v_pk_mul_f32 v[172:173], v[42:43], v[224:225]
	v_fmac_f32_dpp v172, v224, v40 wave_shr:1 row_mask:0xf bank_mask:0xf
	v_fmac_f32_dpp v173, v225, v41 wave_shr:1 row_mask:0xf bank_mask:0xf
	v_fmac_f32_dpp v172, v224, v44 wave_shl:1 row_mask:0xf bank_mask:0xf
	v_fmac_f32_dpp v173, v225, v45 wave_shl:1 row_mask:0xf bank_mask:0xf
	v_pk_add_f32 v[156:157], v[46:47], v[172:173]
	v_pk_mul_f32 v[172:173], v[34:35], v[106:107]
	v_fmac_f32_dpp v172, v106, v32 wave_shr:1 row_mask:0xf bank_mask:0xf
	v_fmac_f32_dpp v173, v107, v33 wave_shr:1 row_mask:0xf bank_mask:0xf
	v_fmac_f32_dpp v172, v106, v36 wave_shl:1 row_mask:0xf bank_mask:0xf
	v_fmac_f32_dpp v173, v107, v37 wave_shl:1 row_mask:0xf bank_mask:0xf
	v_pk_add_f32 v[176:177], v[38:39], v[172:173]
	v_lshlrev_b32_e32 v224, 16, v234
	v_lshlrev_b32_e32 v225, 16, v235
	v_pk_mul_f32 v[172:173], v[42:43], v[224:225]
	v_fmac_f32_dpp v172, v224, v40 wave_shr:1 row_mask:0xf bank_mask:0xf
	v_fmac_f32_dpp v173, v225, v41 wave_shr:1 row_mask:0xf bank_mask:0xf
	v_fmac_f32_dpp v172, v224, v44 wave_shl:1 row_mask:0xf bank_mask:0xf
	v_fmac_f32_dpp v173, v225, v45 wave_shl:1 row_mask:0xf bank_mask:0xf
	v_pk_add_f32 v[158:159], v[46:47], v[172:173]
	v_pk_mul_f32 v[174:175], v[48:49], v[174:175]
	v_pk_fma_f32 v[82:83], v[82:83], s[66:67], v[174:175] op_sel_hi:[1,0,1]
	v_pk_mul_f32 v[82:83], v[82:83], v[156:157]
	v_add_u32_e32 v6, 0x0, v5
	global_store_dwordx2 v6, v[82:83], s[80:81]
	v_pk_mul_f32 v[176:177], v[48:49], v[176:177]
	v_pk_fma_f32 v[84:85], v[84:85], s[66:67], v[176:177] op_sel_hi:[1,0,1]
	v_pk_mul_f32 v[84:85], v[84:85], v[158:159]
	v_add_u32_e32 v6, 0x8000, v5
	global_store_dwordx2 v6, v[84:85], s[80:81]
	global_load_ushort v230, v142, s[12:13] offset:2048
	global_load_ushort v231, v150, s[12:13] offset:2048
	global_load_ushort v234, v144, s[12:13] offset:2048
	global_load_ushort v235, v152, s[12:13] offset:2048
	ds_read_b64 v[12:13], v7 offset:128
	ds_read_b64 v[14:15], v8 offset:8192
	ds_read_b64 v[16:17], v8 offset:40960
	ds_read_b64 v[18:19], v9 offset:8192
	ds_read_b64 v[20:21], v9 offset:40960
	s_waitcnt lgkmcnt(5)
; HD float2 cmul(float2 a, float2 b){ return make_float2(a.x*b.x - a.y*b.y, a.x*b.y + a.y*b.x); }
; HD float2 cmulc(float2 a, float2 b){ return make_float2(a.x*b.x + a.y*b.y, a.y*b.x - a.x*b.y); }
; HD void inv12_half(const float2* Z, const float2* twA, const float2* twB, int t, float2& x0, float2& x1){
;   float2 w1=cmul(twA[t>>6],twB[t&63]), w2=cmul(w1,w1), w3=cmul(w2,w1);
;   float2 b0=Z[t], b1=cmulc(Z[t+4096],w1), b2=cmulc(Z[t+8192],w2), b3=cmulc(Z[t+12288],w3);
;   float2 s02=make_float2(b0.x+b2.x,b0.y+b2.y), d02=make_float2(b0.x-b2.x,b0.y-b2.y);
;   float2 s13=make_float2(b1.x+b3.x,b1.y+b3.y), d13=make_float2(b1.x-b3.x,b1.y-b3.y);
;   x0=make_float2(s02.x+s13.x,s02.y+s13.y);
;   x1=make_float2(d02.x-d13.y,d02.y+d13.x);
; }
; __device__ __forceinline__ void phase_hyena(KP kp_, int hf){ asm volatile("" : "+s"(kp_)); const Params p=load_params(kp_);
;     ...
;         if (st==1){ int tq=tid; asm volatile("" : "+v"(tq));
;           _Pragma("unroll 4") for (int i=0;i<8;++i){ int tb=tq+512*i; float2 xr[2]; inv12_half(Z,twA,twB,tb,xr[0],xr[1]);
;             _Pragma("unroll") for (int hh=0;hh<2;++hh){ int t=tb+hh*4096;
;               float u0=hconv3(rv,t,wv0,wv1,wv2,bv_), u1=hconv3(rv+8192,t,wv0,wv1,wv2,bv_);
;               float x0=hconv3(r1,t,wa0,wa1,wa2,ba_), x1=hconv3(r1+8192,t,wa0,wa1,wa2,ba_);
;               float2 y=xr[hh]; y.x*=(1.f/16384.f); y.y*=(1.f/16384.f);
;               Zs[t]=make_float2(x0*(y.x+u0*bias0), x1*(y.y+u1*bias0)); } }
	v_pk_mul_f32 v[222:223], v[58:59], v[10:11] op_sel:[1,1] op_sel_hi:[1,0]
	v_pk_fma_f32 v[22:23], v[58:59], v[10:11], v[222:223] op_sel:[0,0,0] op_sel_hi:[0,1,1] neg_lo:[0,0,1]
	v_pk_mul_f32 v[222:223], v[22:23], v[22:23] op_sel:[1,1] op_sel_hi:[1,0]
	v_pk_fma_f32 v[24:25], v[22:23], v[22:23], v[222:223] op_sel:[0,0,0] op_sel_hi:[0,1,1] neg_lo:[0,0,1]
	v_pk_mul_f32 v[222:223], v[24:25], v[22:23] op_sel:[1,1] op_sel_hi:[1,0]
	v_pk_fma_f32 v[26:27], v[24:25], v[22:23], v[222:223] op_sel:[0,0,0] op_sel_hi:[0,1,1] neg_lo:[0,0,1]
	v_pk_mul_f32 v[222:223], v[62:63], v[22:23] op_sel:[1,1] op_sel_hi:[0,1]
	v_pk_fma_f32 v[28:29], v[62:63], v[22:23], v[222:223] op_sel:[0,0,0] op_sel_hi:[1,0,1] neg_hi:[0,0,1]
	v_pk_mul_f32 v[222:223], v[64:65], v[24:25] op_sel:[1,1] op_sel_hi:[0,1]
	v_pk_fma_f32 v[30:31], v[64:65], v[24:25], v[222:223] op_sel:[0,0,0] op_sel_hi:[1,0,1] neg_hi:[0,0,1]
	v_pk_mul_f32 v[222:223], v[66:67], v[26:27] op_sel:[1,1] op_sel_hi:[0,1]
	v_pk_fma_f32 v[68:69], v[66:67], v[26:27], v[222:223] op_sel:[0,0,0] op_sel_hi:[1,0,1] neg_hi:[0,0,1]
	v_pk_add_f32 v[70:71], v[60:61], v[30:31]
	v_pk_add_f32 v[72:73], v[60:61], v[30:31] neg_lo:[0,1] neg_hi:[0,1]
	v_pk_add_f32 v[74:75], v[28:29], v[68:69]
	v_pk_add_f32 v[80:81], v[28:29], v[68:69] neg_lo:[0,1] neg_hi:[0,1]
	v_pk_add_f32 v[82:83], v[70:71], v[74:75]
	v_pk_add_f32 v[84:85], v[72:73], v[80:81] op_sel:[0,1] op_sel_hi:[1,0] neg_lo:[0,1]
	s_waitcnt vmcnt(6)
	v_pk_mul_f32 v[172:173], v[34:35], v[108:109]
	v_fmac_f32_dpp v172, v108, v32 wave_shr:1 row_mask:0xf bank_mask:0xf
	v_fmac_f32_dpp v173, v109, v33 wave_shr:1 row_mask:0xf bank_mask:0xf
	v_fmac_f32_dpp v172, v108, v36 wave_shl:1 row_mask:0xf bank_mask:0xf
	v_fmac_f32_dpp v173, v109, v37 wave_shl:1 row_mask:0xf bank_mask:0xf
	v_pk_add_f32 v[174:175], v[38:39], v[172:173]
	v_lshlrev_b32_e32 v224, 16, v242
	v_lshlrev_b32_e32 v225, 16, v243
	v_pk_mul_f32 v[172:173], v[42:43], v[224:225]
	v_fmac_f32_dpp v172, v224, v40 wave_shr:1 row_mask:0xf bank_mask:0xf
	v_fmac_f32_dpp v173, v225, v41 wave_shr:1 row_mask:0xf bank_mask:0xf
	v_fmac_f32_dpp v172, v224, v44 wave_shl:1 row_mask:0xf bank_mask:0xf
	v_fmac_f32_dpp v173, v225, v45 wave_shl:1 row_mask:0xf bank_mask:0xf
	v_pk_add_f32 v[156:157], v[46:47], v[172:173]
	v_pk_mul_f32 v[172:173], v[34:35], v[110:111]
	v_fmac_f32_dpp v172, v110, v32 wave_shr:1 row_mask:0xf bank_mask:0xf
	v_fmac_f32_dpp v173, v111, v33 wave_shr:1 row_mask:0xf bank_mask:0xf
	v_fmac_f32_dpp v172, v110, v36 wave_shl:1 row_mask:0xf bank_mask:0xf
	v_fmac_f32_dpp v173, v111, v37 wave_shl:1 row_mask:0xf bank_mask:0xf
	v_pk_add_f32 v[176:177], v[38:39], v[172:173]
	v_lshlrev_b32_e32 v224, 16, v246
	v_lshlrev_b32_e32 v225, 16, v247
	v_pk_mul_f32 v[172:173], v[42:43], v[224:225]
	v_fmac_f32_dpp v172, v224, v40 wave_shr:1 row_mask:0xf bank_mask:0xf
	v_fmac_f32_dpp v173, v225, v41 wave_shr:1 row_mask:0xf bank_mask:0xf
	v_fmac_f32_dpp v172, v224, v44 wave_shl:1 row_mask:0xf bank_mask:0xf
	v_fmac_f32_dpp v173, v225, v45 wave_shl:1 row_mask:0xf bank_mask:0xf
	v_pk_add_f32 v[158:159], v[46:47], v[172:173]
	v_pk_mul_f32 v[174:175], v[48:49], v[174:175]
	v_pk_fma_f32 v[82:83], v[82:83], s[66:67], v[174:175] op_sel_hi:[1,0,1]
	v_pk_mul_f32 v[82:83], v[82:83], v[156:157]
	v_add_u32_e32 v6, 0x1000, v5
	global_store_dwordx2 v6, v[82:83], s[80:81]
	v_pk_mul_f32 v[176:177], v[48:49], v[176:177]
	v_pk_fma_f32 v[84:85], v[84:85], s[66:67], v[176:177] op_sel_hi:[1,0,1]
	v_pk_mul_f32 v[84:85], v[84:85], v[158:159]
	v_add_u32_e32 v6, 0x9000, v5
	global_store_dwordx2 v6, v[84:85], s[80:81]
	global_load_ushort v242, v142, s[12:13] offset:3072
	global_load_ushort v243, v150, s[12:13] offset:3072
	global_load_ushort v246, v144, s[12:13] offset:3072
	global_load_ushort v247, v152, s[12:13] offset:3072
	ds_read_b64 v[58:59], v7 offset:192
	ds_read_b64 v[60:61], v8 offset:12288
	ds_read_b64 v[62:63], v8 offset:45056
	ds_read_b64 v[64:65], v9 offset:12288
	ds_read_b64 v[66:67], v9 offset:45056
	s_waitcnt lgkmcnt(5)
	v_pk_mul_f32 v[222:223], v[12:13], v[10:11] op_sel:[1,1] op_sel_hi:[1,0]
	v_pk_fma_f32 v[22:23], v[12:13], v[10:11], v[222:223] op_sel:[0,0,0] op_sel_hi:[0,1,1] neg_lo:[0,0,1]
	v_pk_mul_f32 v[222:223], v[22:23], v[22:23] op_sel:[1,1] op_sel_hi:[1,0]
	v_pk_fma_f32 v[24:25], v[22:23], v[22:23], v[222:223] op_sel:[0,0,0] op_sel_hi:[0,1,1] neg_lo:[0,0,1]
	v_pk_mul_f32 v[222:223], v[24:25], v[22:23] op_sel:[1,1] op_sel_hi:[1,0]
	v_pk_fma_f32 v[26:27], v[24:25], v[22:23], v[222:223] op_sel:[0,0,0] op_sel_hi:[0,1,1] neg_lo:[0,0,1]
	v_pk_mul_f32 v[222:223], v[16:17], v[22:23] op_sel:[1,1] op_sel_hi:[0,1]
	v_pk_fma_f32 v[28:29], v[16:17], v[22:23], v[222:223] op_sel:[0,0,0] op_sel_hi:[1,0,1] neg_hi:[0,0,1]
	v_pk_mul_f32 v[222:223], v[18:19], v[24:25] op_sel:[1,1] op_sel_hi:[0,1]
	v_pk_fma_f32 v[30:31], v[18:19], v[24:25], v[222:223] op_sel:[0,0,0] op_sel_hi:[1,0,1] neg_hi:[0,0,1]
	v_pk_mul_f32 v[222:223], v[20:21], v[26:27] op_sel:[1,1] op_sel_hi:[0,1]
	v_pk_fma_f32 v[68:69], v[20:21], v[26:27], v[222:223] op_sel:[0,0,0] op_sel_hi:[1,0,1] neg_hi:[0,0,1]
	v_pk_add_f32 v[70:71], v[14:15], v[30:31]
	v_pk_add_f32 v[72:73], v[14:15], v[30:31] neg_lo:[0,1] neg_hi:[0,1]
	v_pk_add_f32 v[74:75], v[28:29], v[68:69]
	v_pk_add_f32 v[80:81], v[28:29], v[68:69] neg_lo:[0,1] neg_hi:[0,1]
	v_pk_add_f32 v[82:83], v[70:71], v[74:75]
	v_pk_add_f32 v[84:85], v[72:73], v[80:81] op_sel:[0,1] op_sel_hi:[1,0] neg_lo:[0,1]
	s_waitcnt vmcnt(6)
; HD float2 cmul(float2 a, float2 b){ return make_float2(a.x*b.x - a.y*b.y, a.x*b.y + a.y*b.x); }
; HD float2 cmulc(float2 a, float2 b){ return make_float2(a.x*b.x + a.y*b.y, a.y*b.x - a.x*b.y); }
; HD void inv12_half(const float2* Z, const float2* twA, const float2* twB, int t, float2& x0, float2& x1){
;   float2 w1=cmul(twA[t>>6],twB[t&63]), w2=cmul(w1,w1), w3=cmul(w2,w1);
;   float2 b0=Z[t], b1=cmulc(Z[t+4096],w1), b2=cmulc(Z[t+8192],w2), b3=cmulc(Z[t+12288],w3);
;   float2 s02=make_float2(b0.x+b2.x,b0.y+b2.y), d02=make_float2(b0.x-b2.x,b0.y-b2.y);
;   float2 s13=make_float2(b1.x+b3.x,b1.y+b3.y), d13=make_float2(b1.x-b3.x,b1.y-b3.y);
;   x0=make_float2(s02.x+s13.x,s02.y+s13.y);
;   x1=make_float2(d02.x-d13.y,d02.y+d13.x);
; }
; __device__ __forceinline__ void phase_hyena(KP kp_, int hf){ asm volatile("" : "+s"(kp_)); const Params p=load_params(kp_);
;     ...
;         if (st==1){ int tq=tid; asm volatile("" : "+v"(tq));
;           _Pragma("unroll 4") for (int i=0;i<8;++i){ int tb=tq+512*i; float2 xr[2]; inv12_half(Z,twA,twB,tb,xr[0],xr[1]);
;             _Pragma("unroll") for (int hh=0;hh<2;++hh){ int t=tb+hh*4096;
;               float u0=hconv3(rv,t,wv0,wv1,wv2,bv_), u1=hconv3(rv+8192,t,wv0,wv1,wv2,bv_);
;               float x0=hconv3(r1,t,wa0,wa1,wa2,ba_), x1=hconv3(r1+8192,t,wa0,wa1,wa2,ba_);
;               float2 y=xr[hh]; y.x*=(1.f/16384.f); y.y*=(1.f/16384.f);
;               Zs[t]=make_float2(x0*(y.x+u0*bias0), x1*(y.y+u1*bias0)); } }
	v_pk_mul_f32 v[172:173], v[34:35], v[112:113]
	v_fmac_f32_dpp v172, v112, v32 wave_shr:1 row_mask:0xf bank_mask:0xf
	v_fmac_f32_dpp v173, v113, v33 wave_shr:1 row_mask:0xf bank_mask:0xf
	v_fmac_f32_dpp v172, v112, v36 wave_shl:1 row_mask:0xf bank_mask:0xf
	v_fmac_f32_dpp v173, v113, v37 wave_shl:1 row_mask:0xf bank_mask:0xf
	v_pk_add_f32 v[174:175], v[38:39], v[172:173]
	v_lshlrev_b32_e32 v224, 16, v230
	v_lshlrev_b32_e32 v225, 16, v231
	v_pk_mul_f32 v[172:173], v[42:43], v[224:225]
	v_fmac_f32_dpp v172, v224, v40 wave_shr:1 row_mask:0xf bank_mask:0xf
	v_fmac_f32_dpp v173, v225, v41 wave_shr:1 row_mask:0xf bank_mask:0xf
	v_fmac_f32_dpp v172, v224, v44 wave_shl:1 row_mask:0xf bank_mask:0xf
	v_fmac_f32_dpp v173, v225, v45 wave_shl:1 row_mask:0xf bank_mask:0xf
	v_pk_add_f32 v[156:157], v[46:47], v[172:173]
	v_pk_mul_f32 v[172:173], v[34:35], v[114:115]
	v_fmac_f32_dpp v172, v114, v32 wave_shr:1 row_mask:0xf bank_mask:0xf
	v_fmac_f32_dpp v173, v115, v33 wave_shr:1 row_mask:0xf bank_mask:0xf
	v_fmac_f32_dpp v172, v114, v36 wave_shl:1 row_mask:0xf bank_mask:0xf
	v_fmac_f32_dpp v173, v115, v37 wave_shl:1 row_mask:0xf bank_mask:0xf
	v_pk_add_f32 v[176:177], v[38:39], v[172:173]
	v_lshlrev_b32_e32 v224, 16, v234
	v_lshlrev_b32_e32 v225, 16, v235
	v_pk_mul_f32 v[172:173], v[42:43], v[224:225]
	v_fmac_f32_dpp v172, v224, v40 wave_shr:1 row_mask:0xf bank_mask:0xf
	v_fmac_f32_dpp v173, v225, v41 wave_shr:1 row_mask:0xf bank_mask:0xf
	v_fmac_f32_dpp v172, v224, v44 wave_shl:1 row_mask:0xf bank_mask:0xf
	v_fmac_f32_dpp v173, v225, v45 wave_shl:1 row_mask:0xf bank_mask:0xf
	v_pk_add_f32 v[158:159], v[46:47], v[172:173]
	v_pk_mul_f32 v[174:175], v[48:49], v[174:175]
	v_pk_fma_f32 v[82:83], v[82:83], s[66:67], v[174:175] op_sel_hi:[1,0,1]
	v_pk_mul_f32 v[82:83], v[82:83], v[156:157]
	v_add_u32_e32 v6, 0x2000, v5
	global_store_dwordx2 v6, v[82:83], s[80:81]
	v_pk_mul_f32 v[176:177], v[48:49], v[176:177]
	v_pk_fma_f32 v[84:85], v[84:85], s[66:67], v[176:177] op_sel_hi:[1,0,1]
	v_pk_mul_f32 v[84:85], v[84:85], v[158:159]
	v_add_u32_e32 v6, 0xa000, v5
	global_store_dwordx2 v6, v[84:85], s[80:81]
	global_load_ushort v230, v143, s[12:13] offset:0
	global_load_ushort v231, v151, s[12:13] offset:0
	global_load_ushort v234, v145, s[12:13] offset:0
	global_load_ushort v235, v153, s[12:13] offset:0
	ds_read_b64 v[12:13], v7 offset:256
	ds_read_b64 v[14:15], v8 offset:16384
	ds_read_b64 v[16:17], v8 offset:49152
	ds_read_b64 v[18:19], v9 offset:16384
	ds_read_b64 v[20:21], v9 offset:49152
	s_waitcnt lgkmcnt(5)
	v_pk_mul_f32 v[222:223], v[58:59], v[10:11] op_sel:[1,1] op_sel_hi:[1,0]
	v_pk_fma_f32 v[22:23], v[58:59], v[10:11], v[222:223] op_sel:[0,0,0] op_sel_hi:[0,1,1] neg_lo:[0,0,1]
	v_pk_mul_f32 v[222:223], v[22:23], v[22:23] op_sel:[1,1] op_sel_hi:[1,0]
	v_pk_fma_f32 v[24:25], v[22:23], v[22:23], v[222:223] op_sel:[0,0,0] op_sel_hi:[0,1,1] neg_lo:[0,0,1]
	v_pk_mul_f32 v[222:223], v[24:25], v[22:23] op_sel:[1,1] op_sel_hi:[1,0]
	v_pk_fma_f32 v[26:27], v[24:25], v[22:23], v[222:223] op_sel:[0,0,0] op_sel_hi:[0,1,1] neg_lo:[0,0,1]
	v_pk_mul_f32 v[222:223], v[62:63], v[22:23] op_sel:[1,1] op_sel_hi:[0,1]
	v_pk_fma_f32 v[28:29], v[62:63], v[22:23], v[222:223] op_sel:[0,0,0] op_sel_hi:[1,0,1] neg_hi:[0,0,1]
	v_pk_mul_f32 v[222:223], v[64:65], v[24:25] op_sel:[1,1] op_sel_hi:[0,1]
	v_pk_fma_f32 v[30:31], v[64:65], v[24:25], v[222:223] op_sel:[0,0,0] op_sel_hi:[1,0,1] neg_hi:[0,0,1]
	v_pk_mul_f32 v[222:223], v[66:67], v[26:27] op_sel:[1,1] op_sel_hi:[0,1]
	v_pk_fma_f32 v[68:69], v[66:67], v[26:27], v[222:223] op_sel:[0,0,0] op_sel_hi:[1,0,1] neg_hi:[0,0,1]
	v_pk_add_f32 v[70:71], v[60:61], v[30:31]
	v_pk_add_f32 v[72:73], v[60:61], v[30:31] neg_lo:[0,1] neg_hi:[0,1]
	v_pk_add_f32 v[74:75], v[28:29], v[68:69]
	v_pk_add_f32 v[80:81], v[28:29], v[68:69] neg_lo:[0,1] neg_hi:[0,1]
	v_pk_add_f32 v[82:83], v[70:71], v[74:75]
	v_pk_add_f32 v[84:85], v[72:73], v[80:81] op_sel:[0,1] op_sel_hi:[1,0] neg_lo:[0,1]
	s_waitcnt vmcnt(6)
	v_pk_mul_f32 v[172:173], v[34:35], v[116:117]
	v_fmac_f32_dpp v172, v116, v32 wave_shr:1 row_mask:0xf bank_mask:0xf
	v_fmac_f32_dpp v173, v117, v33 wave_shr:1 row_mask:0xf bank_mask:0xf
	v_fmac_f32_dpp v172, v116, v36 wave_shl:1 row_mask:0xf bank_mask:0xf
	v_fmac_f32_dpp v173, v117, v37 wave_shl:1 row_mask:0xf bank_mask:0xf
	v_pk_add_f32 v[174:175], v[38:39], v[172:173]
	v_lshlrev_b32_e32 v224, 16, v242
	v_lshlrev_b32_e32 v225, 16, v243
	v_pk_mul_f32 v[172:173], v[42:43], v[224:225]
	v_fmac_f32_dpp v172, v224, v40 wave_shr:1 row_mask:0xf bank_mask:0xf
	v_fmac_f32_dpp v173, v225, v41 wave_shr:1 row_mask:0xf bank_mask:0xf
	v_fmac_f32_dpp v172, v224, v44 wave_shl:1 row_mask:0xf bank_mask:0xf
	v_fmac_f32_dpp v173, v225, v45 wave_shl:1 row_mask:0xf bank_mask:0xf
	v_pk_add_f32 v[156:157], v[46:47], v[172:173]
	v_pk_mul_f32 v[172:173], v[34:35], v[118:119]
	v_fmac_f32_dpp v172, v118, v32 wave_shr:1 row_mask:0xf bank_mask:0xf
	v_fmac_f32_dpp v173, v119, v33 wave_shr:1 row_mask:0xf bank_mask:0xf
	v_fmac_f32_dpp v172, v118, v36 wave_shl:1 row_mask:0xf bank_mask:0xf
	v_fmac_f32_dpp v173, v119, v37 wave_shl:1 row_mask:0xf bank_mask:0xf
	v_pk_add_f32 v[176:177], v[38:39], v[172:173]
	v_lshlrev_b32_e32 v224, 16, v246
	v_lshlrev_b32_e32 v225, 16, v247
	v_pk_mul_f32 v[172:173], v[42:43], v[224:225]
	v_fmac_f32_dpp v172, v224, v40 wave_shr:1 row_mask:0xf bank_mask:0xf
	v_fmac_f32_dpp v173, v225, v41 wave_shr:1 row_mask:0xf bank_mask:0xf
	v_fmac_f32_dpp v172, v224, v44 wave_shl:1 row_mask:0xf bank_mask:0xf
	v_fmac_f32_dpp v173, v225, v45 wave_shl:1 row_mask:0xf bank_mask:0xf
	v_pk_add_f32 v[158:159], v[46:47], v[172:173]
	v_pk_mul_f32 v[174:175], v[48:49], v[174:175]
	v_pk_fma_f32 v[82:83], v[82:83], s[66:67], v[174:175] op_sel_hi:[1,0,1]
	v_pk_mul_f32 v[82:83], v[82:83], v[156:157]
	v_add_u32_e32 v6, 0x3000, v5
	global_store_dwordx2 v6, v[82:83], s[80:81]
	v_pk_mul_f32 v[176:177], v[48:49], v[176:177]
	v_pk_fma_f32 v[84:85], v[84:85], s[66:67], v[176:177] op_sel_hi:[1,0,1]
	v_pk_mul_f32 v[84:85], v[84:85], v[158:159]
	v_add_u32_e32 v6, 0xb000, v5
	global_store_dwordx2 v6, v[84:85], s[80:81]
	global_load_ushort v242, v143, s[12:13] offset:1024
	global_load_ushort v243, v151, s[12:13] offset:1024
	global_load_ushort v246, v145, s[12:13] offset:1024
	global_load_ushort v247, v153, s[12:13] offset:1024
	ds_read_b64 v[58:59], v7 offset:320
	ds_read_b64 v[60:61], v8 offset:20480
	ds_read_b64 v[62:63], v8 offset:53248
	ds_read_b64 v[64:65], v9 offset:20480
	ds_read_b64 v[66:67], v9 offset:53248
	s_waitcnt lgkmcnt(5)
; HD float2 cmul(float2 a, float2 b){ return make_float2(a.x*b.x - a.y*b.y, a.x*b.y + a.y*b.x); }
; HD float2 cmulc(float2 a, float2 b){ return make_float2(a.x*b.x + a.y*b.y, a.y*b.x - a.x*b.y); }
; HD void inv12_half(const float2* Z, const float2* twA, const float2* twB, int t, float2& x0, float2& x1){
;   float2 w1=cmul(twA[t>>6],twB[t&63]), w2=cmul(w1,w1), w3=cmul(w2,w1);
;   float2 b0=Z[t], b1=cmulc(Z[t+4096],w1), b2=cmulc(Z[t+8192],w2), b3=cmulc(Z[t+12288],w3);
;   float2 s02=make_float2(b0.x+b2.x,b0.y+b2.y), d02=make_float2(b0.x-b2.x,b0.y-b2.y);
;   float2 s13=make_float2(b1.x+b3.x,b1.y+b3.y), d13=make_float2(b1.x-b3.x,b1.y-b3.y);
;   x0=make_float2(s02.x+s13.x,s02.y+s13.y);
;   x1=make_float2(d02.x-d13.y,d02.y+d13.x);
; }
; __device__ __forceinline__ void phase_hyena(KP kp_, int hf){ asm volatile("" : "+s"(kp_)); const Params p=load_params(kp_);
;     ...
;         if (st==1){ int tq=tid; asm volatile("" : "+v"(tq));
;           _Pragma("unroll 4") for (int i=0;i<8;++i){ int tb=tq+512*i; float2 xr[2]; inv12_half(Z,twA,twB,tb,xr[0],xr[1]);
;             _Pragma("unroll") for (int hh=0;hh<2;++hh){ int t=tb+hh*4096;
;               float u0=hconv3(rv,t,wv0,wv1,wv2,bv_), u1=hconv3(rv+8192,t,wv0,wv1,wv2,bv_);
;               float x0=hconv3(r1,t,wa0,wa1,wa2,ba_), x1=hconv3(r1+8192,t,wa0,wa1,wa2,ba_);
;               float2 y=xr[hh]; y.x*=(1.f/16384.f); y.y*=(1.f/16384.f);
;               Zs[t]=make_float2(x0*(y.x+u0*bias0), x1*(y.y+u1*bias0)); } }
	v_pk_mul_f32 v[222:223], v[12:13], v[10:11] op_sel:[1,1] op_sel_hi:[1,0]
	v_pk_fma_f32 v[22:23], v[12:13], v[10:11], v[222:223] op_sel:[0,0,0] op_sel_hi:[0,1,1] neg_lo:[0,0,1]
	v_pk_mul_f32 v[222:223], v[22:23], v[22:23] op_sel:[1,1] op_sel_hi:[1,0]
	v_pk_fma_f32 v[24:25], v[22:23], v[22:23], v[222:223] op_sel:[0,0,0] op_sel_hi:[0,1,1] neg_lo:[0,0,1]
	v_pk_mul_f32 v[222:223], v[24:25], v[22:23] op_sel:[1,1] op_sel_hi:[1,0]
	v_pk_fma_f32 v[26:27], v[24:25], v[22:23], v[222:223] op_sel:[0,0,0] op_sel_hi:[0,1,1] neg_lo:[0,0,1]
	v_pk_mul_f32 v[222:223], v[16:17], v[22:23] op_sel:[1,1] op_sel_hi:[0,1]
	v_pk_fma_f32 v[28:29], v[16:17], v[22:23], v[222:223] op_sel:[0,0,0] op_sel_hi:[1,0,1] neg_hi:[0,0,1]
	v_pk_mul_f32 v[222:223], v[18:19], v[24:25] op_sel:[1,1] op_sel_hi:[0,1]
	v_pk_fma_f32 v[30:31], v[18:19], v[24:25], v[222:223] op_sel:[0,0,0] op_sel_hi:[1,0,1] neg_hi:[0,0,1]
	v_pk_mul_f32 v[222:223], v[20:21], v[26:27] op_sel:[1,1] op_sel_hi:[0,1]
	v_pk_fma_f32 v[68:69], v[20:21], v[26:27], v[222:223] op_sel:[0,0,0] op_sel_hi:[1,0,1] neg_hi:[0,0,1]
	v_pk_add_f32 v[70:71], v[14:15], v[30:31]
	v_pk_add_f32 v[72:73], v[14:15], v[30:31] neg_lo:[0,1] neg_hi:[0,1]
	v_pk_add_f32 v[74:75], v[28:29], v[68:69]
	v_pk_add_f32 v[80:81], v[28:29], v[68:69] neg_lo:[0,1] neg_hi:[0,1]
	v_pk_add_f32 v[82:83], v[70:71], v[74:75]
	v_pk_add_f32 v[84:85], v[72:73], v[80:81] op_sel:[0,1] op_sel_hi:[1,0] neg_lo:[0,1]
	s_waitcnt vmcnt(6)
	v_pk_mul_f32 v[172:173], v[34:35], v[120:121]
	v_fmac_f32_dpp v172, v120, v32 wave_shr:1 row_mask:0xf bank_mask:0xf
	v_fmac_f32_dpp v173, v121, v33 wave_shr:1 row_mask:0xf bank_mask:0xf
	v_fmac_f32_dpp v172, v120, v36 wave_shl:1 row_mask:0xf bank_mask:0xf
	v_fmac_f32_dpp v173, v121, v37 wave_shl:1 row_mask:0xf bank_mask:0xf
	v_pk_add_f32 v[174:175], v[38:39], v[172:173]
	v_lshlrev_b32_e32 v224, 16, v230
	v_lshlrev_b32_e32 v225, 16, v231
	v_pk_mul_f32 v[172:173], v[42:43], v[224:225]
	v_fmac_f32_dpp v172, v224, v40 wave_shr:1 row_mask:0xf bank_mask:0xf
	v_fmac_f32_dpp v173, v225, v41 wave_shr:1 row_mask:0xf bank_mask:0xf
	v_fmac_f32_dpp v172, v224, v44 wave_shl:1 row_mask:0xf bank_mask:0xf
	v_fmac_f32_dpp v173, v225, v45 wave_shl:1 row_mask:0xf bank_mask:0xf
	v_pk_add_f32 v[156:157], v[46:47], v[172:173]
	v_pk_mul_f32 v[172:173], v[34:35], v[122:123]
	v_fmac_f32_dpp v172, v122, v32 wave_shr:1 row_mask:0xf bank_mask:0xf
	v_fmac_f32_dpp v173, v123, v33 wave_shr:1 row_mask:0xf bank_mask:0xf
	v_fmac_f32_dpp v172, v122, v36 wave_shl:1 row_mask:0xf bank_mask:0xf
	v_fmac_f32_dpp v173, v123, v37 wave_shl:1 row_mask:0xf bank_mask:0xf
	v_pk_add_f32 v[176:177], v[38:39], v[172:173]
	v_lshlrev_b32_e32 v224, 16, v234
	v_lshlrev_b32_e32 v225, 16, v235
	v_pk_mul_f32 v[172:173], v[42:43], v[224:225]
	v_fmac_f32_dpp v172, v224, v40 wave_shr:1 row_mask:0xf bank_mask:0xf
	v_fmac_f32_dpp v173, v225, v41 wave_shr:1 row_mask:0xf bank_mask:0xf
	v_fmac_f32_dpp v172, v224, v44 wave_shl:1 row_mask:0xf bank_mask:0xf
	v_fmac_f32_dpp v173, v225, v45 wave_shl:1 row_mask:0xf bank_mask:0xf
	v_pk_add_f32 v[158:159], v[46:47], v[172:173]
	v_pk_mul_f32 v[174:175], v[48:49], v[174:175]
	v_pk_fma_f32 v[82:83], v[82:83], s[66:67], v[174:175] op_sel_hi:[1,0,1]
	v_pk_mul_f32 v[82:83], v[82:83], v[156:157]
	v_add_u32_e32 v6, 0x4000, v5
	global_store_dwordx2 v6, v[82:83], s[80:81]
	v_pk_mul_f32 v[176:177], v[48:49], v[176:177]
	v_pk_fma_f32 v[84:85], v[84:85], s[66:67], v[176:177] op_sel_hi:[1,0,1]
	v_pk_mul_f32 v[84:85], v[84:85], v[158:159]
	v_add_u32_e32 v6, 0xc000, v5
	global_store_dwordx2 v6, v[84:85], s[80:81]
	global_load_ushort v230, v143, s[12:13] offset:2048
	global_load_ushort v231, v151, s[12:13] offset:2048
	global_load_ushort v234, v145, s[12:13] offset:2048
	global_load_ushort v235, v153, s[12:13] offset:2048
	ds_read_b64 v[12:13], v7 offset:384
	ds_read_b64 v[14:15], v8 offset:24576
	ds_read_b64 v[16:17], v8 offset:57344
	ds_read_b64 v[18:19], v9 offset:24576
	ds_read_b64 v[20:21], v9 offset:57344
	s_waitcnt lgkmcnt(5)
	v_pk_mul_f32 v[222:223], v[58:59], v[10:11] op_sel:[1,1] op_sel_hi:[1,0]
	v_pk_fma_f32 v[22:23], v[58:59], v[10:11], v[222:223] op_sel:[0,0,0] op_sel_hi:[0,1,1] neg_lo:[0,0,1]
	v_pk_mul_f32 v[222:223], v[22:23], v[22:23] op_sel:[1,1] op_sel_hi:[1,0]
	v_pk_fma_f32 v[24:25], v[22:23], v[22:23], v[222:223] op_sel:[0,0,0] op_sel_hi:[0,1,1] neg_lo:[0,0,1]
	v_pk_mul_f32 v[222:223], v[24:25], v[22:23] op_sel:[1,1] op_sel_hi:[1,0]
	v_pk_fma_f32 v[26:27], v[24:25], v[22:23], v[222:223] op_sel:[0,0,0] op_sel_hi:[0,1,1] neg_lo:[0,0,1]
	v_pk_mul_f32 v[222:223], v[62:63], v[22:23] op_sel:[1,1] op_sel_hi:[0,1]
	v_pk_fma_f32 v[28:29], v[62:63], v[22:23], v[222:223] op_sel:[0,0,0] op_sel_hi:[1,0,1] neg_hi:[0,0,1]
	v_pk_mul_f32 v[222:223], v[64:65], v[24:25] op_sel:[1,1] op_sel_hi:[0,1]
	v_pk_fma_f32 v[30:31], v[64:65], v[24:25], v[222:223] op_sel:[0,0,0] op_sel_hi:[1,0,1] neg_hi:[0,0,1]
	v_pk_mul_f32 v[222:223], v[66:67], v[26:27] op_sel:[1,1] op_sel_hi:[0,1]
	v_pk_fma_f32 v[68:69], v[66:67], v[26:27], v[222:223] op_sel:[0,0,0] op_sel_hi:[1,0,1] neg_hi:[0,0,1]
	v_pk_add_f32 v[70:71], v[60:61], v[30:31]
	v_pk_add_f32 v[72:73], v[60:61], v[30:31] neg_lo:[0,1] neg_hi:[0,1]
	v_pk_add_f32 v[74:75], v[28:29], v[68:69]
	v_pk_add_f32 v[80:81], v[28:29], v[68:69] neg_lo:[0,1] neg_hi:[0,1]
	v_pk_add_f32 v[82:83], v[70:71], v[74:75]
	v_pk_add_f32 v[84:85], v[72:73], v[80:81] op_sel:[0,1] op_sel_hi:[1,0] neg_lo:[0,1]
	s_waitcnt vmcnt(6)
; HD float2 cmul(float2 a, float2 b){ return make_float2(a.x*b.x - a.y*b.y, a.x*b.y + a.y*b.x); }
; HD float2 cmulc(float2 a, float2 b){ return make_float2(a.x*b.x + a.y*b.y, a.y*b.x - a.x*b.y); }
; HD void inv12_half(const float2* Z, const float2* twA, const float2* twB, int t, float2& x0, float2& x1){
;   float2 w1=cmul(twA[t>>6],twB[t&63]), w2=cmul(w1,w1), w3=cmul(w2,w1);
;   float2 b0=Z[t], b1=cmulc(Z[t+4096],w1), b2=cmulc(Z[t+8192],w2), b3=cmulc(Z[t+12288],w3);
;   float2 s02=make_float2(b0.x+b2.x,b0.y+b2.y), d02=make_float2(b0.x-b2.x,b0.y-b2.y);
;   float2 s13=make_float2(b1.x+b3.x,b1.y+b3.y), d13=make_float2(b1.x-b3.x,b1.y-b3.y);
;   x0=make_float2(s02.x+s13.x,s02.y+s13.y);
;   x1=make_float2(d02.x-d13.y,d02.y+d13.x);
; }
; __device__ __forceinline__ void phase_hyena(KP kp_, int hf){ asm volatile("" : "+s"(kp_)); const Params p=load_params(kp_);
;     ...
;         if (st==1){ int tq=tid; asm volatile("" : "+v"(tq));
;           _Pragma("unroll 4") for (int i=0;i<8;++i){ int tb=tq+512*i; float2 xr[2]; inv12_half(Z,twA,twB,tb,xr[0],xr[1]);
;             _Pragma("unroll") for (int hh=0;hh<2;++hh){ int t=tb+hh*4096;
;               float u0=hconv3(rv,t,wv0,wv1,wv2,bv_), u1=hconv3(rv+8192,t,wv0,wv1,wv2,bv_);
;               float x0=hconv3(r1,t,wa0,wa1,wa2,ba_), x1=hconv3(r1+8192,t,wa0,wa1,wa2,ba_);
;               float2 y=xr[hh]; y.x*=(1.f/16384.f); y.y*=(1.f/16384.f);
;               Zs[t]=make_float2(x0*(y.x+u0*bias0), x1*(y.y+u1*bias0)); } }
	v_pk_mul_f32 v[172:173], v[34:35], v[124:125]
	v_fmac_f32_dpp v172, v124, v32 wave_shr:1 row_mask:0xf bank_mask:0xf
	v_fmac_f32_dpp v173, v125, v33 wave_shr:1 row_mask:0xf bank_mask:0xf
	v_fmac_f32_dpp v172, v124, v36 wave_shl:1 row_mask:0xf bank_mask:0xf
	v_fmac_f32_dpp v173, v125, v37 wave_shl:1 row_mask:0xf bank_mask:0xf
	v_pk_add_f32 v[174:175], v[38:39], v[172:173]
	v_lshlrev_b32_e32 v224, 16, v242
	v_lshlrev_b32_e32 v225, 16, v243
	v_pk_mul_f32 v[172:173], v[42:43], v[224:225]
	v_fmac_f32_dpp v172, v224, v40 wave_shr:1 row_mask:0xf bank_mask:0xf
	v_fmac_f32_dpp v173, v225, v41 wave_shr:1 row_mask:0xf bank_mask:0xf
	v_fmac_f32_dpp v172, v224, v44 wave_shl:1 row_mask:0xf bank_mask:0xf
	v_fmac_f32_dpp v173, v225, v45 wave_shl:1 row_mask:0xf bank_mask:0xf
	v_pk_add_f32 v[156:157], v[46:47], v[172:173]
	v_pk_mul_f32 v[172:173], v[34:35], v[126:127]
	v_fmac_f32_dpp v172, v126, v32 wave_shr:1 row_mask:0xf bank_mask:0xf
	v_fmac_f32_dpp v173, v127, v33 wave_shr:1 row_mask:0xf bank_mask:0xf
	v_fmac_f32_dpp v172, v126, v36 wave_shl:1 row_mask:0xf bank_mask:0xf
	v_fmac_f32_dpp v173, v127, v37 wave_shl:1 row_mask:0xf bank_mask:0xf
	v_pk_add_f32 v[176:177], v[38:39], v[172:173]
	v_lshlrev_b32_e32 v224, 16, v246
	v_lshlrev_b32_e32 v225, 16, v247
	v_pk_mul_f32 v[172:173], v[42:43], v[224:225]
	v_fmac_f32_dpp v172, v224, v40 wave_shr:1 row_mask:0xf bank_mask:0xf
	v_fmac_f32_dpp v173, v225, v41 wave_shr:1 row_mask:0xf bank_mask:0xf
	v_fmac_f32_dpp v172, v224, v44 wave_shl:1 row_mask:0xf bank_mask:0xf
	v_fmac_f32_dpp v173, v225, v45 wave_shl:1 row_mask:0xf bank_mask:0xf
	v_pk_add_f32 v[158:159], v[46:47], v[172:173]
	v_pk_mul_f32 v[174:175], v[48:49], v[174:175]
	v_pk_fma_f32 v[82:83], v[82:83], s[66:67], v[174:175] op_sel_hi:[1,0,1]
	v_pk_mul_f32 v[82:83], v[82:83], v[156:157]
	v_add_u32_e32 v6, 0x5000, v5
	global_store_dwordx2 v6, v[82:83], s[80:81]
	v_pk_mul_f32 v[176:177], v[48:49], v[176:177]
	v_pk_fma_f32 v[84:85], v[84:85], s[66:67], v[176:177] op_sel_hi:[1,0,1]
	v_pk_mul_f32 v[84:85], v[84:85], v[158:159]
	v_add_u32_e32 v6, 0xd000, v5
	global_store_dwordx2 v6, v[84:85], s[80:81]
	global_load_ushort v242, v143, s[12:13] offset:3072
	global_load_ushort v243, v151, s[12:13] offset:3072
	global_load_ushort v246, v145, s[12:13] offset:3072
	global_load_ushort v247, v153, s[12:13] offset:3072
	ds_read_b64 v[58:59], v7 offset:448
	ds_read_b64 v[60:61], v8 offset:28672
	ds_read_b64 v[62:63], v8 offset:61440
	ds_read_b64 v[64:65], v9 offset:28672
	ds_read_b64 v[66:67], v9 offset:61440
	s_waitcnt lgkmcnt(5)
	v_pk_mul_f32 v[222:223], v[12:13], v[10:11] op_sel:[1,1] op_sel_hi:[1,0]
	v_pk_fma_f32 v[22:23], v[12:13], v[10:11], v[222:223] op_sel:[0,0,0] op_sel_hi:[0,1,1] neg_lo:[0,0,1]
	v_pk_mul_f32 v[222:223], v[22:23], v[22:23] op_sel:[1,1] op_sel_hi:[1,0]
	v_pk_fma_f32 v[24:25], v[22:23], v[22:23], v[222:223] op_sel:[0,0,0] op_sel_hi:[0,1,1] neg_lo:[0,0,1]
	v_pk_mul_f32 v[222:223], v[24:25], v[22:23] op_sel:[1,1] op_sel_hi:[1,0]
	v_pk_fma_f32 v[26:27], v[24:25], v[22:23], v[222:223] op_sel:[0,0,0] op_sel_hi:[0,1,1] neg_lo:[0,0,1]
	v_pk_mul_f32 v[222:223], v[16:17], v[22:23] op_sel:[1,1] op_sel_hi:[0,1]
	v_pk_fma_f32 v[28:29], v[16:17], v[22:23], v[222:223] op_sel:[0,0,0] op_sel_hi:[1,0,1] neg_hi:[0,0,1]
	v_pk_mul_f32 v[222:223], v[18:19], v[24:25] op_sel:[1,1] op_sel_hi:[0,1]
	v_pk_fma_f32 v[30:31], v[18:19], v[24:25], v[222:223] op_sel:[0,0,0] op_sel_hi:[1,0,1] neg_hi:[0,0,1]
	v_pk_mul_f32 v[222:223], v[20:21], v[26:27] op_sel:[1,1] op_sel_hi:[0,1]
	v_pk_fma_f32 v[68:69], v[20:21], v[26:27], v[222:223] op_sel:[0,0,0] op_sel_hi:[1,0,1] neg_hi:[0,0,1]
	v_pk_add_f32 v[70:71], v[14:15], v[30:31]
	v_pk_add_f32 v[72:73], v[14:15], v[30:31] neg_lo:[0,1] neg_hi:[0,1]
	v_pk_add_f32 v[74:75], v[28:29], v[68:69]
	v_pk_add_f32 v[80:81], v[28:29], v[68:69] neg_lo:[0,1] neg_hi:[0,1]
	v_pk_add_f32 v[82:83], v[70:71], v[74:75]
	v_pk_add_f32 v[84:85], v[72:73], v[80:81] op_sel:[0,1] op_sel_hi:[1,0] neg_lo:[0,1]
	s_waitcnt vmcnt(6)
; HD float2 cmul(float2 a, float2 b){ return make_float2(a.x*b.x - a.y*b.y, a.x*b.y + a.y*b.x); }
; HD float2 cmulc(float2 a, float2 b){ return make_float2(a.x*b.x + a.y*b.y, a.y*b.x - a.x*b.y); }
; HD void inv12_half(const float2* Z, const float2* twA, const float2* twB, int t, float2& x0, float2& x1){
;   float2 w1=cmul(twA[t>>6],twB[t&63]), w2=cmul(w1,w1), w3=cmul(w2,w1);
;   float2 b0=Z[t], b1=cmulc(Z[t+4096],w1), b2=cmulc(Z[t+8192],w2), b3=cmulc(Z[t+12288],w3);
;   float2 s02=make_float2(b0.x+b2.x,b0.y+b2.y), d02=make_float2(b0.x-b2.x,b0.y-b2.y);
;   float2 s13=make_float2(b1.x+b3.x,b1.y+b3.y), d13=make_float2(b1.x-b3.x,b1.y-b3.y);
;   x0=make_float2(s02.x+s13.x,s02.y+s13.y);
;   x1=make_float2(d02.x-d13.y,d02.y+d13.x);
; }
; __device__ __forceinline__ void phase_hyena(KP kp_, int hf){ asm volatile("" : "+s"(kp_)); const Params p=load_params(kp_);
;     ...
;         if (st==1){ int tq=tid; asm volatile("" : "+v"(tq));
;           _Pragma("unroll 4") for (int i=0;i<8;++i){ int tb=tq+512*i; float2 xr[2]; inv12_half(Z,twA,twB,tb,xr[0],xr[1]);
;             _Pragma("unroll") for (int hh=0;hh<2;++hh){ int t=tb+hh*4096;
;               float u0=hconv3(rv,t,wv0,wv1,wv2,bv_), u1=hconv3(rv+8192,t,wv0,wv1,wv2,bv_);
;               float x0=hconv3(r1,t,wa0,wa1,wa2,ba_), x1=hconv3(r1+8192,t,wa0,wa1,wa2,ba_);
;               float2 y=xr[hh]; y.x*=(1.f/16384.f); y.y*=(1.f/16384.f);
;               Zs[t]=make_float2(x0*(y.x+u0*bias0), x1*(y.y+u1*bias0)); } }
	v_pk_mul_f32 v[172:173], v[34:35], v[134:135]
	v_fmac_f32_dpp v172, v134, v32 wave_shr:1 row_mask:0xf bank_mask:0xf
	v_fmac_f32_dpp v173, v135, v33 wave_shr:1 row_mask:0xf bank_mask:0xf
	v_fmac_f32_dpp v172, v134, v36 wave_shl:1 row_mask:0xf bank_mask:0xf
	v_fmac_f32_dpp v173, v135, v37 wave_shl:1 row_mask:0xf bank_mask:0xf
	v_pk_add_f32 v[174:175], v[38:39], v[172:173]
	v_lshlrev_b32_e32 v224, 16, v230
	v_lshlrev_b32_e32 v225, 16, v231
	v_pk_mul_f32 v[172:173], v[42:43], v[224:225]
	v_fmac_f32_dpp v172, v224, v40 wave_shr:1 row_mask:0xf bank_mask:0xf
	v_fmac_f32_dpp v173, v225, v41 wave_shr:1 row_mask:0xf bank_mask:0xf
	v_fmac_f32_dpp v172, v224, v44 wave_shl:1 row_mask:0xf bank_mask:0xf
	v_fmac_f32_dpp v173, v225, v45 wave_shl:1 row_mask:0xf bank_mask:0xf
	v_pk_add_f32 v[156:157], v[46:47], v[172:173]
	v_pk_mul_f32 v[172:173], v[34:35], v[136:137]
	v_fmac_f32_dpp v172, v136, v32 wave_shr:1 row_mask:0xf bank_mask:0xf
	v_fmac_f32_dpp v173, v137, v33 wave_shr:1 row_mask:0xf bank_mask:0xf
	v_fmac_f32_dpp v172, v136, v36 wave_shl:1 row_mask:0xf bank_mask:0xf
	v_fmac_f32_dpp v173, v137, v37 wave_shl:1 row_mask:0xf bank_mask:0xf
	v_pk_add_f32 v[176:177], v[38:39], v[172:173]
	v_lshlrev_b32_e32 v224, 16, v234
	v_lshlrev_b32_e32 v225, 16, v235
	v_pk_mul_f32 v[172:173], v[42:43], v[224:225]
	v_fmac_f32_dpp v172, v224, v40 wave_shr:1 row_mask:0xf bank_mask:0xf
	v_fmac_f32_dpp v173, v225, v41 wave_shr:1 row_mask:0xf bank_mask:0xf
	v_fmac_f32_dpp v172, v224, v44 wave_shl:1 row_mask:0xf bank_mask:0xf
	v_fmac_f32_dpp v173, v225, v45 wave_shl:1 row_mask:0xf bank_mask:0xf
	v_pk_add_f32 v[158:159], v[46:47], v[172:173]
	v_pk_mul_f32 v[174:175], v[48:49], v[174:175]
	v_pk_fma_f32 v[82:83], v[82:83], s[66:67], v[174:175] op_sel_hi:[1,0,1]
	v_pk_mul_f32 v[82:83], v[82:83], v[156:157]
	v_add_u32_e32 v6, 0x6000, v5
	global_store_dwordx2 v6, v[82:83], s[80:81]
	v_pk_mul_f32 v[176:177], v[48:49], v[176:177]
	v_pk_fma_f32 v[84:85], v[84:85], s[66:67], v[176:177] op_sel_hi:[1,0,1]
	v_pk_mul_f32 v[84:85], v[84:85], v[158:159]
	v_add_u32_e32 v6, 0xe000, v5
	global_store_dwordx2 v6, v[84:85], s[80:81]
	s_waitcnt lgkmcnt(0)
	v_pk_mul_f32 v[222:223], v[58:59], v[10:11] op_sel:[1,1] op_sel_hi:[1,0]
	v_pk_fma_f32 v[22:23], v[58:59], v[10:11], v[222:223] op_sel:[0,0,0] op_sel_hi:[0,1,1] neg_lo:[0,0,1]
	v_pk_mul_f32 v[222:223], v[22:23], v[22:23] op_sel:[1,1] op_sel_hi:[1,0]
	v_pk_fma_f32 v[24:25], v[22:23], v[22:23], v[222:223] op_sel:[0,0,0] op_sel_hi:[0,1,1] neg_lo:[0,0,1]
	v_pk_mul_f32 v[222:223], v[24:25], v[22:23] op_sel:[1,1] op_sel_hi:[1,0]
	v_pk_fma_f32 v[26:27], v[24:25], v[22:23], v[222:223] op_sel:[0,0,0] op_sel_hi:[0,1,1] neg_lo:[0,0,1]
	v_pk_mul_f32 v[222:223], v[62:63], v[22:23] op_sel:[1,1] op_sel_hi:[0,1]
	v_pk_fma_f32 v[28:29], v[62:63], v[22:23], v[222:223] op_sel:[0,0,0] op_sel_hi:[1,0,1] neg_hi:[0,0,1]
	v_pk_mul_f32 v[222:223], v[64:65], v[24:25] op_sel:[1,1] op_sel_hi:[0,1]
	v_pk_fma_f32 v[30:31], v[64:65], v[24:25], v[222:223] op_sel:[0,0,0] op_sel_hi:[1,0,1] neg_hi:[0,0,1]
	v_pk_mul_f32 v[222:223], v[66:67], v[26:27] op_sel:[1,1] op_sel_hi:[0,1]
	v_pk_fma_f32 v[68:69], v[66:67], v[26:27], v[222:223] op_sel:[0,0,0] op_sel_hi:[1,0,1] neg_hi:[0,0,1]
	v_pk_add_f32 v[70:71], v[60:61], v[30:31]
	v_pk_add_f32 v[72:73], v[60:61], v[30:31] neg_lo:[0,1] neg_hi:[0,1]
	v_pk_add_f32 v[74:75], v[28:29], v[68:69]
	v_pk_add_f32 v[80:81], v[28:29], v[68:69] neg_lo:[0,1] neg_hi:[0,1]
	v_pk_add_f32 v[82:83], v[70:71], v[74:75]
	v_pk_add_f32 v[84:85], v[72:73], v[80:81] op_sel:[0,1] op_sel_hi:[1,0] neg_lo:[0,1]
	s_waitcnt vmcnt(2)
	v_pk_mul_f32 v[172:173], v[34:35], v[138:139]
	v_fmac_f32_dpp v172, v138, v32 wave_shr:1 row_mask:0xf bank_mask:0xf
	v_fmac_f32_dpp v173, v139, v33 wave_shr:1 row_mask:0xf bank_mask:0xf
	v_fmac_f32_dpp v172, v138, v36 wave_shl:1 row_mask:0xf bank_mask:0xf
	v_fmac_f32_dpp v173, v139, v37 wave_shl:1 row_mask:0xf bank_mask:0xf
	v_pk_add_f32 v[174:175], v[38:39], v[172:173]
	v_lshlrev_b32_e32 v224, 16, v242
	v_lshlrev_b32_e32 v225, 16, v243
	v_pk_mul_f32 v[172:173], v[42:43], v[224:225]
	v_fmac_f32_dpp v172, v224, v40 wave_shr:1 row_mask:0xf bank_mask:0xf
	v_fmac_f32_dpp v173, v225, v41 wave_shr:1 row_mask:0xf bank_mask:0xf
	v_fmac_f32_dpp v172, v224, v44 wave_shl:1 row_mask:0xf bank_mask:0xf
	v_fmac_f32_dpp v173, v225, v45 wave_shl:1 row_mask:0xf bank_mask:0xf
	v_pk_add_f32 v[156:157], v[46:47], v[172:173]
	v_pk_mul_f32 v[172:173], v[34:35], v[140:141]
	v_fmac_f32_dpp v172, v140, v32 wave_shr:1 row_mask:0xf bank_mask:0xf
	v_fmac_f32_dpp v173, v141, v33 wave_shr:1 row_mask:0xf bank_mask:0xf
	v_fmac_f32_dpp v172, v140, v36 wave_shl:1 row_mask:0xf bank_mask:0xf
	v_fmac_f32_dpp v173, v141, v37 wave_shl:1 row_mask:0xf bank_mask:0xf
	v_pk_add_f32 v[176:177], v[38:39], v[172:173]
	v_lshlrev_b32_e32 v224, 16, v246
	v_lshlrev_b32_e32 v225, 16, v247
	v_pk_mul_f32 v[172:173], v[42:43], v[224:225]
	v_fmac_f32_dpp v172, v224, v40 wave_shr:1 row_mask:0xf bank_mask:0xf
	v_fmac_f32_dpp v173, v225, v41 wave_shr:1 row_mask:0xf bank_mask:0xf
	v_fmac_f32_dpp v172, v224, v44 wave_shl:1 row_mask:0xf bank_mask:0xf
	v_fmac_f32_dpp v173, v225, v45 wave_shl:1 row_mask:0xf bank_mask:0xf
	v_pk_add_f32 v[158:159], v[46:47], v[172:173]
	v_pk_mul_f32 v[174:175], v[48:49], v[174:175]
	v_pk_fma_f32 v[82:83], v[82:83], s[66:67], v[174:175] op_sel_hi:[1,0,1]
	v_pk_mul_f32 v[82:83], v[82:83], v[156:157]
	v_add_u32_e32 v6, 0x7000, v5
	global_store_dwordx2 v6, v[82:83], s[80:81]
	v_pk_mul_f32 v[176:177], v[48:49], v[176:177]
	v_pk_fma_f32 v[84:85], v[84:85], s[66:67], v[176:177] op_sel_hi:[1,0,1]
	v_pk_mul_f32 v[84:85], v[84:85], v[158:159]
	v_add_u32_e32 v6, 0xf000, v5
	global_store_dwordx2 v6, v[84:85], s[80:81]
	s_mov_b32 s12, 0x8000
